# baseline (speedup 1.0000x reference)
.LBB0_138:
	s_add_u32 s8, s6, s65
	s_addc_u32 s9, s7, s66
	s_mov_b32 m0, s76
	s_add_u32 s98, s8, s44
	s_addc_u32 s99, s9, s45
	global_load_lds_dwordx4 v129, s[98:99]
	s_mov_b32 m0, s75
	s_nop 0
	global_load_lds_dwordx4 v130, s[98:99]
	ds_read_b128 v[140:143], v138
	ds_read_b128 v[144:147], v138 offset:1024
	ds_read_b128 v[148:151], v138 offset:2048
	ds_read_b128 v[152:155], v138 offset:3072
	ds_read_b128 v[156:159], v134
	ds_read_b128 v[160:163], v134 offset:1024
	ds_read_b128 v[164:167], v133
	ds_read_b128 v[168:171], v133 offset:1024
	ds_read_b128 v[172:175], v132
	ds_read_b128 v[176:179], v132 offset:1024
	ds_read_b128 v[180:183], v131
	ds_read_b128 v[184:187], v131 offset:1024
	s_waitcnt lgkmcnt(8)
	s_barrier
	s_waitcnt lgkmcnt(7)
	v_mfma_f32_16x16x32_bf16 v[124:127], v[140:143], v[156:159], v[124:127]
	v_mfma_f32_16x16x32_bf16 v[120:123], v[148:151], v[156:159], v[120:123]
	s_waitcnt lgkmcnt(5)
	v_mfma_f32_16x16x32_bf16 v[116:119], v[140:143], v[164:167], v[116:119]
	v_mfma_f32_16x16x32_bf16 v[112:115], v[148:151], v[164:167], v[112:115]
	s_waitcnt lgkmcnt(3)
	v_mfma_f32_16x16x32_bf16 v[108:111], v[140:143], v[172:175], v[108:111]
	v_mfma_f32_16x16x32_bf16 v[104:107], v[148:151], v[172:175], v[104:107]
	s_waitcnt lgkmcnt(1)
	v_mfma_f32_16x16x32_bf16 v[100:103], v[140:143], v[180:183], v[100:103]
	v_mfma_f32_16x16x32_bf16 v[96:99], v[148:151], v[180:183], v[96:99]
	v_mfma_f32_16x16x32_bf16 v[124:127], v[144:147], v[160:163], v[124:127]
	v_mfma_f32_16x16x32_bf16 v[120:123], v[152:155], v[160:163], v[120:123]
	v_mfma_f32_16x16x32_bf16 v[116:119], v[144:147], v[168:171], v[116:119]
	v_mfma_f32_16x16x32_bf16 v[112:115], v[152:155], v[168:171], v[112:115]
	v_mfma_f32_16x16x32_bf16 v[108:111], v[144:147], v[176:179], v[108:111]
	v_mfma_f32_16x16x32_bf16 v[104:107], v[152:155], v[176:179], v[104:107]
	s_waitcnt lgkmcnt(0)
	v_mfma_f32_16x16x32_bf16 v[100:103], v[144:147], v[184:187], v[100:103]
	v_mfma_f32_16x16x32_bf16 v[96:99], v[152:155], v[184:187], v[96:99]
	s_barrier
	s_add_u32 s10, s6, s36
	s_addc_u32 s11, s7, s37
	s_mov_b32 m0, s63
	s_add_u32 s98, s10, s46
	s_addc_u32 s99, s11, s47
	global_load_lds_dwordx4 v129, s[98:99]
	s_mov_b32 m0, s64
	s_nop 0
	global_load_lds_dwordx4 v130, s[98:99]
	ds_read_b128 v[188:191], v137
	ds_read_b128 v[192:195], v137 offset:1024
	ds_read_b128 v[202:205], v137 offset:2048
	ds_read_b128 v[206:209], v137 offset:3072
	s_barrier
	s_waitcnt lgkmcnt(3)
	v_mfma_f32_16x16x32_bf16 v[92:95], v[188:191], v[156:159], v[92:95]
	s_waitcnt lgkmcnt(1)
	v_mfma_f32_16x16x32_bf16 v[88:91], v[202:205], v[156:159], v[88:91]
	v_mfma_f32_16x16x32_bf16 v[84:87], v[188:191], v[164:167], v[84:87]
	v_mfma_f32_16x16x32_bf16 v[80:83], v[202:205], v[164:167], v[80:83]
	v_mfma_f32_16x16x32_bf16 v[76:79], v[188:191], v[172:175], v[76:79]
	v_mfma_f32_16x16x32_bf16 v[72:75], v[202:205], v[172:175], v[72:75]
	v_mfma_f32_16x16x32_bf16 v[68:71], v[188:191], v[180:183], v[68:71]
	v_mfma_f32_16x16x32_bf16 v[64:67], v[202:205], v[180:183], v[64:67]
	v_mfma_f32_16x16x32_bf16 v[92:95], v[192:195], v[160:163], v[92:95]
	s_waitcnt lgkmcnt(0)
	v_mfma_f32_16x16x32_bf16 v[88:91], v[206:209], v[160:163], v[88:91]
	v_mfma_f32_16x16x32_bf16 v[84:87], v[192:195], v[168:171], v[84:87]
	v_mfma_f32_16x16x32_bf16 v[80:83], v[206:209], v[168:171], v[80:83]
	v_mfma_f32_16x16x32_bf16 v[76:79], v[192:195], v[176:179], v[76:79]
	v_mfma_f32_16x16x32_bf16 v[72:75], v[206:209], v[176:179], v[72:75]
	v_mfma_f32_16x16x32_bf16 v[68:71], v[192:195], v[184:187], v[68:71]
	v_mfma_f32_16x16x32_bf16 v[64:67], v[206:209], v[184:187], v[64:67]
	s_barrier
	s_mov_b32 m0, s62
	s_add_u32 s98, s8, s48
	s_addc_u32 s99, s9, s49
	global_load_lds_dwordx4 v129, s[98:99]
	s_mov_b32 m0, s67
	s_nop 0
	global_load_lds_dwordx4 v130, s[98:99]
	ds_read_b128 v[156:159], v134 offset:16384
	ds_read_b128 v[160:163], v134 offset:17408
	ds_read_b128 v[164:167], v133 offset:16384
	ds_read_b128 v[168:171], v133 offset:17408
	ds_read_b128 v[172:175], v132 offset:16384
	ds_read_b128 v[176:179], v132 offset:17408
	ds_read_b128 v[180:183], v131 offset:16384
	ds_read_b128 v[184:187], v131 offset:17408
	s_barrier
	s_waitcnt lgkmcnt(7)
	v_mfma_f32_16x16x32_bf16 v[60:63], v[140:143], v[156:159], v[60:63]
	v_mfma_f32_16x16x32_bf16 v[56:59], v[148:151], v[156:159], v[56:59]
	s_waitcnt lgkmcnt(5)
	v_mfma_f32_16x16x32_bf16 v[52:55], v[140:143], v[164:167], v[52:55]
	v_mfma_f32_16x16x32_bf16 v[48:51], v[148:151], v[164:167], v[48:51]
	s_waitcnt lgkmcnt(3)
	v_mfma_f32_16x16x32_bf16 v[44:47], v[140:143], v[172:175], v[44:47]
	v_mfma_f32_16x16x32_bf16 v[40:43], v[148:151], v[172:175], v[40:43]
	s_waitcnt lgkmcnt(1)
	v_mfma_f32_16x16x32_bf16 v[36:39], v[140:143], v[180:183], v[36:39]
	v_mfma_f32_16x16x32_bf16 v[32:35], v[148:151], v[180:183], v[32:35]
	v_mfma_f32_16x16x32_bf16 v[60:63], v[144:147], v[160:163], v[60:63]
	v_mfma_f32_16x16x32_bf16 v[56:59], v[152:155], v[160:163], v[56:59]
	v_mfma_f32_16x16x32_bf16 v[52:55], v[144:147], v[168:171], v[52:55]
	v_mfma_f32_16x16x32_bf16 v[48:51], v[152:155], v[168:171], v[48:51]
	v_mfma_f32_16x16x32_bf16 v[44:47], v[144:147], v[176:179], v[44:47]
	v_mfma_f32_16x16x32_bf16 v[40:43], v[152:155], v[176:179], v[40:43]
	s_waitcnt lgkmcnt(0)
	v_mfma_f32_16x16x32_bf16 v[36:39], v[144:147], v[184:187], v[36:39]
	v_mfma_f32_16x16x32_bf16 v[32:35], v[152:155], v[184:187], v[32:35]
	s_barrier
	s_mov_b32 m0, s68
	s_add_u32 s98, s10, s50
	s_addc_u32 s99, s11, s51
	global_load_lds_dwordx4 v129, s[98:99]
	s_mov_b32 m0, s69
	s_nop 0
	global_load_lds_dwordx4 v130, s[98:99]
	s_waitcnt vmcnt(6)
	s_barrier
	v_mfma_f32_16x16x32_bf16 v[28:31], v[188:191], v[156:159], v[28:31]
	v_mfma_f32_16x16x32_bf16 v[24:27], v[202:205], v[156:159], v[24:27]
	v_mfma_f32_16x16x32_bf16 v[20:23], v[188:191], v[164:167], v[20:23]
	v_mfma_f32_16x16x32_bf16 v[16:19], v[202:205], v[164:167], v[16:19]
	v_mfma_f32_16x16x32_bf16 v[12:15], v[188:191], v[172:175], v[12:15]
	v_mfma_f32_16x16x32_bf16 v[8:11], v[202:205], v[172:175], v[8:11]
	v_mfma_f32_16x16x32_bf16 v[4:7], v[188:191], v[180:183], v[4:7]
	v_mfma_f32_16x16x32_bf16 v[0:3], v[202:205], v[180:183], v[0:3]
	v_mfma_f32_16x16x32_bf16 v[28:31], v[192:195], v[160:163], v[28:31]
	v_mfma_f32_16x16x32_bf16 v[24:27], v[206:209], v[160:163], v[24:27]
	v_mfma_f32_16x16x32_bf16 v[20:23], v[192:195], v[168:171], v[20:23]
	v_mfma_f32_16x16x32_bf16 v[16:19], v[206:209], v[168:171], v[16:19]
	v_mfma_f32_16x16x32_bf16 v[12:15], v[192:195], v[176:179], v[12:15]
	v_mfma_f32_16x16x32_bf16 v[8:11], v[206:209], v[176:179], v[8:11]
	v_mfma_f32_16x16x32_bf16 v[4:7], v[192:195], v[184:187], v[4:7]
	v_mfma_f32_16x16x32_bf16 v[0:3], v[206:209], v[184:187], v[0:3]
	s_barrier
	s_mov_b32 m0, s70
	s_add_u32 s98, s8, s90
	s_addc_u32 s99, s9, s91
	global_load_lds_dwordx4 v129, s[98:99]
	s_mov_b32 m0, s71
	s_nop 0
	global_load_lds_dwordx4 v130, s[98:99]
	ds_read_b128 v[140:143], v136
	ds_read_b128 v[144:147], v136 offset:1024
	ds_read_b128 v[148:151], v136 offset:2048
	ds_read_b128 v[152:155], v136 offset:3072
	ds_read_b128 v[156:159], v134 offset:32768
	ds_read_b128 v[160:163], v134 offset:33792
	ds_read_b128 v[164:167], v133 offset:32768
	ds_read_b128 v[168:171], v133 offset:33792
	ds_read_b128 v[172:175], v132 offset:32768
	ds_read_b128 v[176:179], v132 offset:33792
	ds_read_b128 v[180:183], v131 offset:32768
	ds_read_b128 v[184:187], v131 offset:33792
	s_waitcnt lgkmcnt(8)
	s_barrier
	s_waitcnt lgkmcnt(7)
	v_mfma_f32_16x16x32_bf16 v[124:127], v[140:143], v[156:159], v[124:127]
	v_mfma_f32_16x16x32_bf16 v[120:123], v[148:151], v[156:159], v[120:123]
	s_waitcnt lgkmcnt(5)
	v_mfma_f32_16x16x32_bf16 v[116:119], v[140:143], v[164:167], v[116:119]
	v_mfma_f32_16x16x32_bf16 v[112:115], v[148:151], v[164:167], v[112:115]
	s_waitcnt lgkmcnt(3)
	v_mfma_f32_16x16x32_bf16 v[108:111], v[140:143], v[172:175], v[108:111]
	v_mfma_f32_16x16x32_bf16 v[104:107], v[148:151], v[172:175], v[104:107]
	s_waitcnt lgkmcnt(1)
	v_mfma_f32_16x16x32_bf16 v[100:103], v[140:143], v[180:183], v[100:103]
	v_mfma_f32_16x16x32_bf16 v[96:99], v[148:151], v[180:183], v[96:99]
	v_mfma_f32_16x16x32_bf16 v[124:127], v[144:147], v[160:163], v[124:127]
	v_mfma_f32_16x16x32_bf16 v[120:123], v[152:155], v[160:163], v[120:123]
	v_mfma_f32_16x16x32_bf16 v[116:119], v[144:147], v[168:171], v[116:119]
	v_mfma_f32_16x16x32_bf16 v[112:115], v[152:155], v[168:171], v[112:115]
	v_mfma_f32_16x16x32_bf16 v[108:111], v[144:147], v[176:179], v[108:111]
	v_mfma_f32_16x16x32_bf16 v[104:107], v[152:155], v[176:179], v[104:107]
	s_waitcnt lgkmcnt(0)
	v_mfma_f32_16x16x32_bf16 v[100:103], v[144:147], v[184:187], v[100:103]
	v_mfma_f32_16x16x32_bf16 v[96:99], v[152:155], v[184:187], v[96:99]
	s_barrier
	s_mov_b32 m0, s28
	s_add_u32 s98, s10, s92
	s_addc_u32 s99, s11, s93
	global_load_lds_dwordx4 v129, s[98:99]
	s_mov_b32 m0, s29
	s_nop 0
	global_load_lds_dwordx4 v130, s[98:99]
	ds_read_b128 v[188:191], v135
	ds_read_b128 v[192:195], v135 offset:1024
	ds_read_b128 v[202:205], v135 offset:2048
	ds_read_b128 v[206:209], v135 offset:3072
	s_barrier
	s_waitcnt lgkmcnt(3)
	v_mfma_f32_16x16x32_bf16 v[92:95], v[188:191], v[156:159], v[92:95]
	s_waitcnt lgkmcnt(1)
	v_mfma_f32_16x16x32_bf16 v[88:91], v[202:205], v[156:159], v[88:91]
	v_mfma_f32_16x16x32_bf16 v[84:87], v[188:191], v[164:167], v[84:87]
	v_mfma_f32_16x16x32_bf16 v[80:83], v[202:205], v[164:167], v[80:83]
	v_mfma_f32_16x16x32_bf16 v[76:79], v[188:191], v[172:175], v[76:79]
	v_mfma_f32_16x16x32_bf16 v[72:75], v[202:205], v[172:175], v[72:75]
	v_mfma_f32_16x16x32_bf16 v[68:71], v[188:191], v[180:183], v[68:71]
	v_mfma_f32_16x16x32_bf16 v[64:67], v[202:205], v[180:183], v[64:67]
	v_mfma_f32_16x16x32_bf16 v[92:95], v[192:195], v[160:163], v[92:95]
	s_waitcnt lgkmcnt(0)
	v_mfma_f32_16x16x32_bf16 v[88:91], v[206:209], v[160:163], v[88:91]
	v_mfma_f32_16x16x32_bf16 v[84:87], v[192:195], v[168:171], v[84:87]
	v_mfma_f32_16x16x32_bf16 v[80:83], v[206:209], v[168:171], v[80:83]
	v_mfma_f32_16x16x32_bf16 v[76:79], v[192:195], v[176:179], v[76:79]
	v_mfma_f32_16x16x32_bf16 v[72:75], v[206:209], v[176:179], v[72:75]
	v_mfma_f32_16x16x32_bf16 v[68:71], v[192:195], v[184:187], v[68:71]
	v_mfma_f32_16x16x32_bf16 v[64:67], v[206:209], v[184:187], v[64:67]
	v_mov_b32_e32 v210, v130
	s_barrier
	ds_read_b128 v[156:159], v134 offset:49152
	ds_read_b128 v[160:163], v134 offset:50176
	ds_read_b128 v[164:167], v133 offset:49152
	ds_read_b128 v[168:171], v133 offset:50176
	ds_read_b128 v[172:175], v132 offset:49152
	ds_read_b128 v[176:179], v132 offset:50176
	ds_read_b128 v[180:183], v131 offset:49152
	ds_read_b128 v[184:187], v131 offset:50176
	v_mov_b32_e32 v211, v197
	s_mov_b32 m0, s72
	s_add_u32 s98, s8, s96
	s_addc_u32 s99, s9, s97
	global_load_lds_dwordx4 v129, s[98:99]
	s_mov_b32 m0, s73
	s_nop 0
	global_load_lds_dwordx4 v130, s[98:99]
	s_barrier
	s_waitcnt lgkmcnt(7)
	v_mfma_f32_16x16x32_bf16 v[60:63], v[140:143], v[156:159], v[60:63]
	v_mfma_f32_16x16x32_bf16 v[56:59], v[148:151], v[156:159], v[56:59]
	s_waitcnt lgkmcnt(5)
	v_mfma_f32_16x16x32_bf16 v[52:55], v[140:143], v[164:167], v[52:55]
	v_mfma_f32_16x16x32_bf16 v[48:51], v[148:151], v[164:167], v[48:51]
	s_waitcnt lgkmcnt(3)
	v_mfma_f32_16x16x32_bf16 v[44:47], v[140:143], v[172:175], v[44:47]
	v_mfma_f32_16x16x32_bf16 v[40:43], v[148:151], v[172:175], v[40:43]
	s_waitcnt lgkmcnt(1)
	v_mfma_f32_16x16x32_bf16 v[36:39], v[140:143], v[180:183], v[36:39]
	v_mfma_f32_16x16x32_bf16 v[32:35], v[148:151], v[180:183], v[32:35]
	v_mfma_f32_16x16x32_bf16 v[60:63], v[144:147], v[160:163], v[60:63]
	v_mfma_f32_16x16x32_bf16 v[56:59], v[152:155], v[160:163], v[56:59]
	v_mfma_f32_16x16x32_bf16 v[52:55], v[144:147], v[168:171], v[52:55]
	v_mfma_f32_16x16x32_bf16 v[48:51], v[152:155], v[168:171], v[48:51]
	v_mfma_f32_16x16x32_bf16 v[44:47], v[144:147], v[176:179], v[44:47]
	v_mfma_f32_16x16x32_bf16 v[40:43], v[152:155], v[176:179], v[40:43]
	s_waitcnt lgkmcnt(0)
	v_mfma_f32_16x16x32_bf16 v[36:39], v[144:147], v[184:187], v[36:39]
	v_mfma_f32_16x16x32_bf16 v[32:35], v[152:155], v[184:187], v[32:35]
	s_barrier
	v_mov_b32_e32 v196, v129
	s_mov_b32 m0, s33
	s_add_u32 s98, s10, vcc_lo
	s_addc_u32 s99, s11, vcc_hi
	global_load_lds_dwordx4 v129, s[98:99]
	s_mov_b32 m0, s74
	s_nop 0
	global_load_lds_dwordx4 v130, s[98:99]
	s_waitcnt vmcnt(6)
	s_barrier
	v_mfma_f32_16x16x32_bf16 v[28:31], v[188:191], v[156:159], v[28:31]
	v_mfma_f32_16x16x32_bf16 v[24:27], v[202:205], v[156:159], v[24:27]
	v_mfma_f32_16x16x32_bf16 v[20:23], v[188:191], v[164:167], v[20:23]
	v_mfma_f32_16x16x32_bf16 v[16:19], v[202:205], v[164:167], v[16:19]
	v_mfma_f32_16x16x32_bf16 v[12:15], v[188:191], v[172:175], v[12:15]
	v_mfma_f32_16x16x32_bf16 v[8:11], v[202:205], v[172:175], v[8:11]
	v_mfma_f32_16x16x32_bf16 v[4:7], v[188:191], v[180:183], v[4:7]
	v_mfma_f32_16x16x32_bf16 v[0:3], v[202:205], v[180:183], v[0:3]
	v_mfma_f32_16x16x32_bf16 v[28:31], v[192:195], v[160:163], v[28:31]
	v_mfma_f32_16x16x32_bf16 v[24:27], v[206:209], v[160:163], v[24:27]
	v_mfma_f32_16x16x32_bf16 v[20:23], v[192:195], v[168:171], v[20:23]
	v_mfma_f32_16x16x32_bf16 v[16:19], v[206:209], v[168:171], v[16:19]
	v_mfma_f32_16x16x32_bf16 v[12:15], v[192:195], v[176:179], v[12:15]
	v_mfma_f32_16x16x32_bf16 v[8:11], v[206:209], v[176:179], v[8:11]
	v_mfma_f32_16x16x32_bf16 v[4:7], v[192:195], v[184:187], v[4:7]
	v_mfma_f32_16x16x32_bf16 v[0:3], v[206:209], v[184:187], v[0:3]
	s_add_i32 s38, s38, 2
	s_add_u32 s6, s6, 0x100
	s_addc_u32 s7, s7, 0
	s_cmpk_lt_u32 s38, 0x54
	s_barrier
	s_cbranch_scc1 .LBB0_138
	s_add_u32 s4, s4, 0x2b80
	s_addc_u32 s5, s5, 0
	s_mov_b32 m0, s76
	ds_read_b128 v[140:143], v138
	ds_read_b128 v[144:147], v138 offset:1024
	ds_read_b128 v[148:151], v138 offset:2048
	ds_read_b128 v[152:155], v138 offset:3072
	ds_read_b128 v[156:159], v134
	ds_read_b128 v[160:163], v134 offset:1024
	ds_read_b128 v[164:167], v133
	ds_read_b128 v[168:171], v133 offset:1024
	ds_read_b128 v[172:175], v132
	ds_read_b128 v[176:179], v132 offset:1024
	ds_read_b128 v[180:183], v131
	ds_read_b128 v[184:187], v131 offset:1024
	s_nop 0
	global_load_lds_dwordx4 v129, s[4:5]
	s_mov_b32 m0, s75
	s_nop 0
	global_load_lds_dwordx4 v130, s[4:5]
	s_barrier
	s_waitcnt lgkmcnt(0)
	s_setprio 1
	s_waitcnt lgkmcnt(0)
	v_mfma_f32_16x16x32_bf16 v[124:127], v[140:143], v[156:159], v[124:127]
	v_mfma_f32_16x16x32_bf16 v[120:123], v[148:151], v[156:159], v[120:123]
	v_mfma_f32_16x16x32_bf16 v[116:119], v[140:143], v[164:167], v[116:119]
	v_mfma_f32_16x16x32_bf16 v[112:115], v[148:151], v[164:167], v[112:115]
	v_mfma_f32_16x16x32_bf16 v[108:111], v[140:143], v[172:175], v[108:111]
	v_mfma_f32_16x16x32_bf16 v[100:103], v[140:143], v[180:183], v[100:103]
	v_mfma_f32_16x16x32_bf16 v[96:99], v[148:151], v[180:183], v[96:99]
	v_mfma_f32_16x16x32_bf16 v[124:127], v[144:147], v[160:163], v[124:127]
	v_mfma_f32_16x16x32_bf16 v[120:123], v[152:155], v[160:163], v[120:123]
	v_mfma_f32_16x16x32_bf16 v[116:119], v[144:147], v[168:171], v[116:119]
	v_mfma_f32_16x16x32_bf16 v[112:115], v[152:155], v[168:171], v[112:115]
	v_mfma_f32_16x16x32_bf16 v[108:111], v[144:147], v[176:179], v[108:111]
	v_mfma_f32_16x16x32_bf16 v[104:107], v[148:151], v[172:175], v[104:107]
	v_mfma_f32_16x16x32_bf16 v[100:103], v[144:147], v[184:187], v[100:103]
	v_mfma_f32_16x16x32_bf16 v[96:99], v[152:155], v[184:187], v[96:99]
	v_mfma_f32_16x16x32_bf16 v[188:191], v[152:155], v[176:179], v[104:107]
	s_setprio 0
	s_barrier
	s_nop 2
	ds_read_b128 v[104:107], v137
	ds_read_b128 v[192:195], v137 offset:1024
	ds_read_b128 v[202:205], v137 offset:2048
	ds_read_b128 v[206:209], v137 offset:3072
	s_barrier
	s_waitcnt lgkmcnt(0)
	s_setprio 1
	s_waitcnt lgkmcnt(0)
	v_mfma_f32_16x16x32_bf16 v[92:95], v[104:107], v[156:159], v[92:95]
	v_mfma_f32_16x16x32_bf16 v[88:91], v[202:205], v[156:159], v[88:91]
	v_mfma_f32_16x16x32_bf16 v[80:83], v[202:205], v[164:167], v[80:83]
	v_mfma_f32_16x16x32_bf16 v[72:75], v[202:205], v[172:175], v[72:75]
	v_mfma_f32_16x16x32_bf16 v[64:67], v[202:205], v[180:183], v[64:67]
	v_mfma_f32_16x16x32_bf16 v[92:95], v[192:195], v[160:163], v[92:95]
	v_mfma_f32_16x16x32_bf16 v[88:91], v[206:209], v[160:163], v[88:91]
	v_mfma_f32_16x16x32_bf16 v[84:87], v[104:107], v[164:167], v[84:87]
	v_mfma_f32_16x16x32_bf16 v[80:83], v[206:209], v[168:171], v[80:83]
	v_mfma_f32_16x16x32_bf16 v[76:79], v[104:107], v[172:175], v[76:79]
	v_mfma_f32_16x16x32_bf16 v[72:75], v[206:209], v[176:179], v[72:75]
	v_mfma_f32_16x16x32_bf16 v[68:71], v[104:107], v[180:183], v[68:71]
	v_mfma_f32_16x16x32_bf16 v[64:67], v[206:209], v[184:187], v[64:67]
	v_mfma_f32_16x16x32_bf16 v[156:159], v[192:195], v[168:171], v[84:87]
	v_mfma_f32_16x16x32_bf16 v[160:163], v[192:195], v[176:179], v[76:79]
	v_mfma_f32_16x16x32_bf16 v[164:167], v[192:195], v[184:187], v[68:71]
	s_setprio 0
	s_barrier
	s_nop 1
	ds_read_b128 v[68:71], v134 offset:16384
	ds_read_b128 v[76:79], v134 offset:17408
	ds_read_b128 v[84:87], v133 offset:16384
	ds_read_b128 v[168:171], v133 offset:17408
	ds_read_b128 v[172:175], v132 offset:16384
	ds_read_b128 v[176:179], v132 offset:17408
	ds_read_b128 v[180:183], v131 offset:16384
	ds_read_b128 v[184:187], v131 offset:17408
	s_waitcnt vmcnt(4)
	s_barrier
	s_waitcnt lgkmcnt(0)
	s_setprio 1
	s_waitcnt lgkmcnt(0)
	v_mfma_f32_16x16x32_bf16 v[60:63], v[140:143], v[68:71], v[60:63]
	v_mfma_f32_16x16x32_bf16 v[56:59], v[148:151], v[68:71], v[56:59]
	v_mfma_f32_16x16x32_bf16 v[48:51], v[148:151], v[84:87], v[48:51]
	v_mfma_f32_16x16x32_bf16 v[32:35], v[148:151], v[180:183], v[32:35]
	v_mfma_f32_16x16x32_bf16 v[60:63], v[144:147], v[76:79], v[60:63]
	v_mfma_f32_16x16x32_bf16 v[56:59], v[152:155], v[76:79], v[56:59]
	v_mfma_f32_16x16x32_bf16 v[52:55], v[140:143], v[84:87], v[52:55]
	v_mfma_f32_16x16x32_bf16 v[48:51], v[152:155], v[168:171], v[48:51]
	v_mfma_f32_16x16x32_bf16 v[44:47], v[140:143], v[172:175], v[44:47]
	v_mfma_f32_16x16x32_bf16 v[40:43], v[148:151], v[172:175], v[40:43]
	v_mfma_f32_16x16x32_bf16 v[36:39], v[140:143], v[180:183], v[36:39]
	v_mfma_f32_16x16x32_bf16 v[32:35], v[152:155], v[184:187], v[32:35]
	v_mfma_f32_16x16x32_bf16 v[210:213], v[144:147], v[168:171], v[52:55]
	v_mfma_f32_16x16x32_bf16 v[214:217], v[144:147], v[176:179], v[44:47]
	v_mfma_f32_16x16x32_bf16 v[218:221], v[152:155], v[176:179], v[40:43]
	v_mfma_f32_16x16x32_bf16 v[138:141], v[144:147], v[184:187], v[36:39]
	s_setprio 0
	s_setprio 1
	v_mfma_f32_16x16x32_bf16 v[24:27], v[202:205], v[68:71], v[24:27]
	v_mfma_f32_16x16x32_bf16 v[20:23], v[104:107], v[84:87], v[20:23]
	v_mfma_f32_16x16x32_bf16 v[28:31], v[104:107], v[68:71], v[28:31]
	v_mfma_f32_16x16x32_bf16 v[24:27], v[206:209], v[76:79], v[24:27]
	v_mfma_f32_16x16x32_bf16 v[20:23], v[192:195], v[168:171], v[20:23]
	v_mfma_f32_16x16x32_bf16 v[16:19], v[202:205], v[84:87], v[16:19]
	v_mfma_f32_16x16x32_bf16 v[12:15], v[104:107], v[172:175], v[12:15]
	v_mfma_f32_16x16x32_bf16 v[8:11], v[202:205], v[172:175], v[8:11]
	v_mfma_f32_16x16x32_bf16 v[4:7], v[104:107], v[180:183], v[4:7]
	v_mfma_f32_16x16x32_bf16 v[0:3], v[202:205], v[180:183], v[0:3]
	v_mfma_f32_16x16x32_bf16 v[142:145], v[192:195], v[76:79], v[28:31]
	v_mfma_f32_16x16x32_bf16 v[146:149], v[206:209], v[168:171], v[16:19]
	v_mfma_f32_16x16x32_bf16 v[150:153], v[192:195], v[176:179], v[12:15]
	v_mfma_f32_16x16x32_bf16 v[168:171], v[206:209], v[176:179], v[8:11]
	v_mfma_f32_16x16x32_bf16 v[172:175], v[192:195], v[184:187], v[4:7]
	v_mfma_f32_16x16x32_bf16 v[176:179], v[206:209], v[184:187], v[0:3]
	s_setprio 0
	s_barrier
	ds_read_b128 v[16:19], v136
	ds_read_b128 v[180:183], v136 offset:1024
	ds_read_b128 v[184:187], v136 offset:2048
	ds_read_b128 v[192:195], v136 offset:3072
	ds_read_b128 v[0:3], v134 offset:32768
	ds_read_b128 v[4:7], v134 offset:33792
	ds_read_b128 v[8:11], v133 offset:32768
	ds_read_b128 v[12:15], v133 offset:33792
	ds_read_b128 v[44:47], v132 offset:32768
	ds_read_b128 v[202:205], v132 offset:33792
	ds_read_b128 v[206:209], v131 offset:32768
	ds_read_b128 v[222:225], v131 offset:33792
	s_waitcnt vmcnt(2)
	s_barrier
	s_waitcnt lgkmcnt(0)
	s_setprio 1
	s_waitcnt lgkmcnt(0)
	v_mfma_f32_16x16x32_bf16 v[28:31], v[16:19], v[0:3], v[124:127]
	v_mfma_f32_16x16x32_bf16 v[52:55], v[180:183], v[4:7], v[28:31]
	v_mfma_f32_16x16x32_bf16 v[28:31], v[184:187], v[0:3], v[120:123]
	v_mfma_f32_16x16x32_bf16 v[104:107], v[192:195], v[4:7], v[28:31]
	v_mfma_f32_16x16x32_bf16 v[28:31], v[16:19], v[8:11], v[116:119]
	v_mfma_f32_16x16x32_bf16 v[68:71], v[180:183], v[12:15], v[28:31]
	v_mfma_f32_16x16x32_bf16 v[28:31], v[184:187], v[8:11], v[112:115]
	v_mfma_f32_16x16x32_bf16 v[116:119], v[192:195], v[12:15], v[28:31]
	v_mfma_f32_16x16x32_bf16 v[28:31], v[16:19], v[44:47], v[108:111]
	v_mfma_f32_16x16x32_bf16 v[76:79], v[180:183], v[202:205], v[28:31]
	v_mfma_f32_16x16x32_bf16 v[28:31], v[184:187], v[44:47], v[188:191]
	v_mfma_f32_16x16x32_bf16 v[108:111], v[192:195], v[202:205], v[28:31]
	v_mfma_f32_16x16x32_bf16 v[28:31], v[16:19], v[206:209], v[100:103]
	v_mfma_f32_16x16x32_bf16 v[84:87], v[180:183], v[222:225], v[28:31]
	v_mfma_f32_16x16x32_bf16 v[28:31], v[184:187], v[206:209], v[96:99]
	v_mfma_f32_16x16x32_bf16 v[96:99], v[192:195], v[222:225], v[28:31]
	s_setprio 0
	s_barrier
	ds_read_b128 v[188:191], v135
	ds_read_b128 v[228:231], v135 offset:1024
	ds_read_b128 v[232:235], v135 offset:2048
	ds_read_b128 v[236:239], v135 offset:3072
	s_waitcnt vmcnt(0)
	s_barrier
	s_waitcnt lgkmcnt(0)
	s_setprio 1
	s_waitcnt lgkmcnt(0)
	v_mfma_f32_16x16x32_bf16 v[28:31], v[188:191], v[0:3], v[92:95]
	v_mfma_f32_16x16x32_bf16 v[0:3], v[232:235], v[0:3], v[88:91]
	v_mfma_f32_16x16x32_bf16 v[28:31], v[228:231], v[4:7], v[28:31]
	v_mfma_f32_16x16x32_bf16 v[0:3], v[236:239], v[4:7], v[0:3]
	v_mfma_f32_16x16x32_bf16 v[4:7], v[188:191], v[8:11], v[156:159]
	v_mfma_f32_16x16x32_bf16 v[36:39], v[228:231], v[12:15], v[4:7]
	v_mfma_f32_16x16x32_bf16 v[4:7], v[232:235], v[8:11], v[80:83]
	v_mfma_f32_16x16x32_bf16 v[4:7], v[236:239], v[12:15], v[4:7]
	v_mfma_f32_16x16x32_bf16 v[8:11], v[188:191], v[44:47], v[160:163]
	v_mfma_f32_16x16x32_bf16 v[12:15], v[188:191], v[206:209], v[164:167]
	v_mfma_f32_16x16x32_bf16 v[40:43], v[228:231], v[202:205], v[8:11]
	v_mfma_f32_16x16x32_bf16 v[8:11], v[232:235], v[44:47], v[72:75]
	v_mfma_f32_16x16x32_bf16 v[44:47], v[228:231], v[222:225], v[12:15]
	v_mfma_f32_16x16x32_bf16 v[12:15], v[232:235], v[206:209], v[64:67]
	v_mfma_f32_16x16x32_bf16 v[8:11], v[236:239], v[202:205], v[8:11]
	v_mfma_f32_16x16x32_bf16 v[12:15], v[236:239], v[222:225], v[12:15]
	s_setprio 0
	s_barrier
	ds_read_b128 v[64:67], v134 offset:49152
	ds_read_b128 v[134:137], v134 offset:50176
	ds_read_b128 v[154:157], v133 offset:49152
	ds_read_b128 v[158:161], v133 offset:50176
	ds_read_b128 v[162:165], v132 offset:49152
	ds_read_b128 v[202:205], v132 offset:50176
	ds_read_b128 v[206:209], v131 offset:49152
	ds_read_b128 v[130:133], v131 offset:50176
	s_barrier
	s_waitcnt lgkmcnt(0)
	s_setprio 1
	s_waitcnt lgkmcnt(0)
	v_mfma_f32_16x16x32_bf16 v[56:59], v[184:187], v[64:67], v[56:59]
	v_mfma_f32_16x16x32_bf16 v[48:51], v[184:187], v[154:157], v[48:51]
	v_mfma_f32_16x16x32_bf16 v[60:63], v[16:19], v[64:67], v[60:63]
	v_mfma_f32_16x16x32_bf16 v[92:95], v[192:195], v[134:137], v[56:59]
	v_mfma_f32_16x16x32_bf16 v[56:59], v[16:19], v[154:157], v[210:213]
	v_mfma_f32_16x16x32_bf16 v[88:91], v[192:195], v[158:161], v[48:51]
	v_mfma_f32_16x16x32_bf16 v[48:51], v[16:19], v[162:165], v[214:217]
	v_mfma_f32_16x16x32_bf16 v[16:19], v[16:19], v[206:209], v[138:141]
	v_mfma_f32_16x16x32_bf16 v[120:123], v[180:183], v[202:205], v[48:51]
	v_mfma_f32_16x16x32_bf16 v[48:51], v[184:187], v[162:165], v[218:221]
	v_mfma_f32_16x16x32_bf16 v[124:127], v[180:183], v[130:133], v[16:19]
	v_mfma_f32_16x16x32_bf16 v[16:19], v[184:187], v[206:209], v[32:35]
	v_mfma_f32_16x16x32_bf16 v[100:103], v[180:183], v[134:137], v[60:63]
	v_mfma_f32_16x16x32_bf16 v[112:115], v[180:183], v[158:161], v[56:59]
	v_mfma_f32_16x16x32_bf16 v[80:83], v[192:195], v[202:205], v[48:51]
	v_mfma_f32_16x16x32_bf16 v[72:75], v[192:195], v[130:133], v[16:19]
	s_setprio 0
	s_setprio 1
	v_mfma_f32_16x16x32_bf16 v[16:19], v[188:191], v[64:67], v[142:145]
	v_mfma_f32_16x16x32_bf16 v[48:51], v[228:231], v[134:137], v[16:19]
	v_mfma_f32_16x16x32_bf16 v[16:19], v[232:235], v[64:67], v[24:27]
	v_mfma_f32_16x16x32_bf16 v[20:23], v[188:191], v[154:157], v[20:23]
	v_mfma_f32_16x16x32_bf16 v[24:27], v[188:191], v[162:165], v[150:153]
	v_mfma_f32_16x16x32_bf16 v[32:35], v[188:191], v[206:209], v[172:175]
	v_mfma_f32_16x16x32_bf16 v[56:59], v[228:231], v[158:161], v[20:23]
	v_mfma_f32_16x16x32_bf16 v[20:23], v[232:235], v[154:157], v[146:149]
	v_mfma_f32_16x16x32_bf16 v[60:63], v[228:231], v[202:205], v[24:27]
	v_mfma_f32_16x16x32_bf16 v[24:27], v[232:235], v[162:165], v[168:171]
	v_mfma_f32_16x16x32_bf16 v[64:67], v[228:231], v[130:133], v[32:35]
	v_mfma_f32_16x16x32_bf16 v[32:35], v[232:235], v[206:209], v[176:179]
	v_mfma_f32_16x16x32_bf16 v[16:19], v[236:239], v[134:137], v[16:19]
	v_mfma_f32_16x16x32_bf16 v[20:23], v[236:239], v[158:161], v[20:23]
	v_mfma_f32_16x16x32_bf16 v[24:27], v[236:239], v[202:205], v[24:27]
	v_mfma_f32_16x16x32_bf16 v[32:35], v[236:239], v[130:133], v[32:35]
	s_setprio 0
	s_movk_i32 s4, 0x100
	v_cmp_gt_u32_e32 vcc, s4, v128
	s_barrier
	s_and_saveexec_b64 s[4:5], vcc
	s_cbranch_execz .LBB0_95
	s_barrier
	s_branch .LBB0_95

.LBB0_192:
	s_add_u32 s28, s56, s4
	s_addc_u32 s29, s57, s5
	s_add_i32 s40, s52, 0xc000
	s_mov_b32 m0, s40
	s_add_i32 s39, s52, 0xe000
	s_add_u32 s98, s28, s44
	s_addc_u32 s99, s29, s45
	global_load_lds_dwordx4 v128, s[98:99]
	s_mov_b32 m0, s39
	s_nop 0
	global_load_lds_dwordx4 v130, s[98:99]
	ds_read_b128 v[140:143], v129
	ds_read_b128 v[144:147], v129 offset:1024
	ds_read_b128 v[148:151], v129 offset:2048
	ds_read_b128 v[152:155], v129 offset:3072
	ds_read_b128 v[156:159], v136
	ds_read_b128 v[160:163], v136 offset:1024
	ds_read_b128 v[164:167], v135
	ds_read_b128 v[168:171], v135 offset:1024
	ds_read_b128 v[172:175], v134
	ds_read_b128 v[176:179], v134 offset:1024
	ds_read_b128 v[180:183], v133
	ds_read_b128 v[184:187], v133 offset:1024
	s_waitcnt lgkmcnt(8)
	s_barrier
	s_waitcnt lgkmcnt(7)
	v_mfma_f32_16x16x32_bf16 v[124:127], v[140:143], v[156:159], v[124:127]
	v_mfma_f32_16x16x32_bf16 v[120:123], v[148:151], v[156:159], v[120:123]
	s_waitcnt lgkmcnt(5)
	v_mfma_f32_16x16x32_bf16 v[116:119], v[140:143], v[164:167], v[116:119]
	v_mfma_f32_16x16x32_bf16 v[112:115], v[148:151], v[164:167], v[112:115]
	s_waitcnt lgkmcnt(3)
	v_mfma_f32_16x16x32_bf16 v[108:111], v[140:143], v[172:175], v[108:111]
	v_mfma_f32_16x16x32_bf16 v[104:107], v[148:151], v[172:175], v[104:107]
	s_waitcnt lgkmcnt(1)
	v_mfma_f32_16x16x32_bf16 v[100:103], v[140:143], v[180:183], v[100:103]
	v_mfma_f32_16x16x32_bf16 v[96:99], v[148:151], v[180:183], v[96:99]
	v_mfma_f32_16x16x32_bf16 v[124:127], v[144:147], v[160:163], v[124:127]
	v_mfma_f32_16x16x32_bf16 v[120:123], v[152:155], v[160:163], v[120:123]
	v_mfma_f32_16x16x32_bf16 v[116:119], v[144:147], v[168:171], v[116:119]
	v_mfma_f32_16x16x32_bf16 v[112:115], v[152:155], v[168:171], v[112:115]
	v_mfma_f32_16x16x32_bf16 v[108:111], v[144:147], v[176:179], v[108:111]
	v_mfma_f32_16x16x32_bf16 v[104:107], v[152:155], v[176:179], v[104:107]
	s_waitcnt lgkmcnt(0)
	v_mfma_f32_16x16x32_bf16 v[100:103], v[144:147], v[184:187], v[100:103]
	v_mfma_f32_16x16x32_bf16 v[96:99], v[152:155], v[184:187], v[96:99]
	s_barrier
	s_add_u32 s58, s56, s36
	s_addc_u32 s59, s57, s37
	s_add_i32 m0, s52, 0x10000
	s_add_u32 s98, s58, s46
	s_addc_u32 s99, s59, s47
	global_load_lds_dwordx4 v128, s[98:99]
	s_add_i32 m0, s52, 0x12000
	s_nop 0
	global_load_lds_dwordx4 v130, s[98:99]
	ds_read_b128 v[188:191], v139
	ds_read_b128 v[192:195], v139 offset:1024
	ds_read_b128 v[202:205], v139 offset:2048
	ds_read_b128 v[206:209], v139 offset:3072
	s_barrier
	s_waitcnt lgkmcnt(3)
	v_mfma_f32_16x16x32_bf16 v[92:95], v[188:191], v[156:159], v[92:95]
	s_waitcnt lgkmcnt(1)
	v_mfma_f32_16x16x32_bf16 v[88:91], v[202:205], v[156:159], v[88:91]
	v_mfma_f32_16x16x32_bf16 v[84:87], v[188:191], v[164:167], v[84:87]
	v_mfma_f32_16x16x32_bf16 v[80:83], v[202:205], v[164:167], v[80:83]
	v_mfma_f32_16x16x32_bf16 v[76:79], v[188:191], v[172:175], v[76:79]
	v_mfma_f32_16x16x32_bf16 v[72:75], v[202:205], v[172:175], v[72:75]
	v_mfma_f32_16x16x32_bf16 v[68:71], v[188:191], v[180:183], v[68:71]
	v_mfma_f32_16x16x32_bf16 v[64:67], v[202:205], v[180:183], v[64:67]
	v_mfma_f32_16x16x32_bf16 v[92:95], v[192:195], v[160:163], v[92:95]
	s_waitcnt lgkmcnt(0)
	v_mfma_f32_16x16x32_bf16 v[88:91], v[206:209], v[160:163], v[88:91]
	v_mfma_f32_16x16x32_bf16 v[84:87], v[192:195], v[168:171], v[84:87]
	v_mfma_f32_16x16x32_bf16 v[80:83], v[206:209], v[168:171], v[80:83]
	v_mfma_f32_16x16x32_bf16 v[76:79], v[192:195], v[176:179], v[76:79]
	v_mfma_f32_16x16x32_bf16 v[72:75], v[206:209], v[176:179], v[72:75]
	v_mfma_f32_16x16x32_bf16 v[68:71], v[192:195], v[184:187], v[68:71]
	v_mfma_f32_16x16x32_bf16 v[64:67], v[206:209], v[184:187], v[64:67]
	s_barrier
	s_mov_b32 m0, s52
	s_add_u32 s98, s28, s48
	s_addc_u32 s99, s29, s49
	global_load_lds_dwordx4 v128, s[98:99]
	s_add_i32 m0, s52, 0x2000
	s_nop 0
	global_load_lds_dwordx4 v130, s[98:99]
	ds_read_b128 v[156:159], v136 offset:16384
	ds_read_b128 v[160:163], v136 offset:17408
	ds_read_b128 v[164:167], v135 offset:16384
	ds_read_b128 v[168:171], v135 offset:17408
	ds_read_b128 v[172:175], v134 offset:16384
	ds_read_b128 v[176:179], v134 offset:17408
	ds_read_b128 v[180:183], v133 offset:16384
	ds_read_b128 v[184:187], v133 offset:17408
	s_barrier
	s_waitcnt lgkmcnt(7)
	v_mfma_f32_16x16x32_bf16 v[60:63], v[140:143], v[156:159], v[60:63]
	v_mfma_f32_16x16x32_bf16 v[56:59], v[148:151], v[156:159], v[56:59]
	s_waitcnt lgkmcnt(5)
	v_mfma_f32_16x16x32_bf16 v[52:55], v[140:143], v[164:167], v[52:55]
	v_mfma_f32_16x16x32_bf16 v[48:51], v[148:151], v[164:167], v[48:51]
	s_waitcnt lgkmcnt(3)
	v_mfma_f32_16x16x32_bf16 v[44:47], v[140:143], v[172:175], v[44:47]
	v_mfma_f32_16x16x32_bf16 v[40:43], v[148:151], v[172:175], v[40:43]
	s_waitcnt lgkmcnt(1)
	v_mfma_f32_16x16x32_bf16 v[36:39], v[140:143], v[180:183], v[36:39]
	v_mfma_f32_16x16x32_bf16 v[32:35], v[148:151], v[180:183], v[32:35]
	v_mfma_f32_16x16x32_bf16 v[60:63], v[144:147], v[160:163], v[60:63]
	v_mfma_f32_16x16x32_bf16 v[56:59], v[152:155], v[160:163], v[56:59]
	v_mfma_f32_16x16x32_bf16 v[52:55], v[144:147], v[168:171], v[52:55]
	v_mfma_f32_16x16x32_bf16 v[48:51], v[152:155], v[168:171], v[48:51]
	v_mfma_f32_16x16x32_bf16 v[44:47], v[144:147], v[176:179], v[44:47]
	v_mfma_f32_16x16x32_bf16 v[40:43], v[152:155], v[176:179], v[40:43]
	s_waitcnt lgkmcnt(0)
	v_mfma_f32_16x16x32_bf16 v[36:39], v[144:147], v[184:187], v[36:39]
	v_mfma_f32_16x16x32_bf16 v[32:35], v[152:155], v[184:187], v[32:35]
	s_barrier
	s_add_i32 m0, s52, 0x14000
	s_add_u32 s98, s58, s50
	s_addc_u32 s99, s59, s51
	global_load_lds_dwordx4 v128, s[98:99]
	s_add_i32 m0, s52, 0x16000
	s_nop 0
	global_load_lds_dwordx4 v130, s[98:99]
	s_waitcnt vmcnt(6)
	s_barrier
	v_mfma_f32_16x16x32_bf16 v[28:31], v[188:191], v[156:159], v[28:31]
	v_mfma_f32_16x16x32_bf16 v[24:27], v[202:205], v[156:159], v[24:27]
	v_mfma_f32_16x16x32_bf16 v[20:23], v[188:191], v[164:167], v[20:23]
	v_mfma_f32_16x16x32_bf16 v[16:19], v[202:205], v[164:167], v[16:19]
	v_mfma_f32_16x16x32_bf16 v[12:15], v[188:191], v[172:175], v[12:15]
	v_mfma_f32_16x16x32_bf16 v[8:11], v[202:205], v[172:175], v[8:11]
	v_mfma_f32_16x16x32_bf16 v[4:7], v[188:191], v[180:183], v[4:7]
	v_mfma_f32_16x16x32_bf16 v[0:3], v[202:205], v[180:183], v[0:3]
	v_mfma_f32_16x16x32_bf16 v[28:31], v[192:195], v[160:163], v[28:31]
	v_mfma_f32_16x16x32_bf16 v[24:27], v[206:209], v[160:163], v[24:27]
	v_mfma_f32_16x16x32_bf16 v[20:23], v[192:195], v[168:171], v[20:23]
	v_mfma_f32_16x16x32_bf16 v[16:19], v[206:209], v[168:171], v[16:19]
	v_mfma_f32_16x16x32_bf16 v[12:15], v[192:195], v[176:179], v[12:15]
	v_mfma_f32_16x16x32_bf16 v[8:11], v[206:209], v[176:179], v[8:11]
	v_mfma_f32_16x16x32_bf16 v[4:7], v[192:195], v[184:187], v[4:7]
	v_mfma_f32_16x16x32_bf16 v[0:3], v[206:209], v[184:187], v[0:3]
	s_barrier
	s_add_i32 m0, s52, 0x4000
	s_add_u32 s98, s28, s54
	s_addc_u32 s99, s29, s55
	global_load_lds_dwordx4 v128, s[98:99]
	s_add_i32 m0, s52, 0x6000
	s_nop 0
	global_load_lds_dwordx4 v130, s[98:99]
	ds_read_b128 v[140:143], v138
	ds_read_b128 v[144:147], v138 offset:1024
	ds_read_b128 v[148:151], v138 offset:2048
	ds_read_b128 v[152:155], v138 offset:3072
	ds_read_b128 v[156:159], v136 offset:32768
	ds_read_b128 v[160:163], v136 offset:33792
	ds_read_b128 v[164:167], v135 offset:32768
	ds_read_b128 v[168:171], v135 offset:33792
	ds_read_b128 v[172:175], v134 offset:32768
	ds_read_b128 v[176:179], v134 offset:33792
	ds_read_b128 v[180:183], v133 offset:32768
	ds_read_b128 v[184:187], v133 offset:33792
	s_waitcnt lgkmcnt(8)
	s_barrier
	s_waitcnt lgkmcnt(7)
	v_mfma_f32_16x16x32_bf16 v[124:127], v[140:143], v[156:159], v[124:127]
	v_mfma_f32_16x16x32_bf16 v[120:123], v[148:151], v[156:159], v[120:123]
	s_waitcnt lgkmcnt(5)
	v_mfma_f32_16x16x32_bf16 v[116:119], v[140:143], v[164:167], v[116:119]
	v_mfma_f32_16x16x32_bf16 v[112:115], v[148:151], v[164:167], v[112:115]
	s_waitcnt lgkmcnt(3)
	v_mfma_f32_16x16x32_bf16 v[108:111], v[140:143], v[172:175], v[108:111]
	v_mfma_f32_16x16x32_bf16 v[104:107], v[148:151], v[172:175], v[104:107]
	s_waitcnt lgkmcnt(1)
	v_mfma_f32_16x16x32_bf16 v[100:103], v[140:143], v[180:183], v[100:103]
	v_mfma_f32_16x16x32_bf16 v[96:99], v[148:151], v[180:183], v[96:99]
	v_mfma_f32_16x16x32_bf16 v[124:127], v[144:147], v[160:163], v[124:127]
	v_mfma_f32_16x16x32_bf16 v[120:123], v[152:155], v[160:163], v[120:123]
	v_mfma_f32_16x16x32_bf16 v[116:119], v[144:147], v[168:171], v[116:119]
	v_mfma_f32_16x16x32_bf16 v[112:115], v[152:155], v[168:171], v[112:115]
	v_mfma_f32_16x16x32_bf16 v[108:111], v[144:147], v[176:179], v[108:111]
	v_mfma_f32_16x16x32_bf16 v[104:107], v[152:155], v[176:179], v[104:107]
	s_waitcnt lgkmcnt(0)
	v_mfma_f32_16x16x32_bf16 v[100:103], v[144:147], v[184:187], v[100:103]
	v_mfma_f32_16x16x32_bf16 v[96:99], v[152:155], v[184:187], v[96:99]
	s_barrier
	s_mov_b32 m0, s7
	s_add_u32 s98, s58, s68
	s_addc_u32 s99, s59, s69
	global_load_lds_dwordx4 v128, s[98:99]
	s_mov_b32 m0, s53
	s_nop 0
	global_load_lds_dwordx4 v130, s[98:99]
	ds_read_b128 v[188:191], v137
	ds_read_b128 v[192:195], v137 offset:1024
	ds_read_b128 v[202:205], v137 offset:2048
	ds_read_b128 v[206:209], v137 offset:3072
	s_barrier
	s_waitcnt lgkmcnt(3)
	v_mfma_f32_16x16x32_bf16 v[92:95], v[188:191], v[156:159], v[92:95]
	s_waitcnt lgkmcnt(1)
	v_mfma_f32_16x16x32_bf16 v[88:91], v[202:205], v[156:159], v[88:91]
	v_mfma_f32_16x16x32_bf16 v[84:87], v[188:191], v[164:167], v[84:87]
	v_mfma_f32_16x16x32_bf16 v[80:83], v[202:205], v[164:167], v[80:83]
	v_mfma_f32_16x16x32_bf16 v[76:79], v[188:191], v[172:175], v[76:79]
	v_mfma_f32_16x16x32_bf16 v[72:75], v[202:205], v[172:175], v[72:75]
	v_mfma_f32_16x16x32_bf16 v[68:71], v[188:191], v[180:183], v[68:71]
	v_mfma_f32_16x16x32_bf16 v[64:67], v[202:205], v[180:183], v[64:67]
	v_mfma_f32_16x16x32_bf16 v[92:95], v[192:195], v[160:163], v[92:95]
	s_waitcnt lgkmcnt(0)
	v_mfma_f32_16x16x32_bf16 v[88:91], v[206:209], v[160:163], v[88:91]
	v_mfma_f32_16x16x32_bf16 v[84:87], v[192:195], v[168:171], v[84:87]
	v_mfma_f32_16x16x32_bf16 v[80:83], v[206:209], v[168:171], v[80:83]
	v_mfma_f32_16x16x32_bf16 v[76:79], v[192:195], v[176:179], v[76:79]
	v_mfma_f32_16x16x32_bf16 v[72:75], v[206:209], v[176:179], v[72:75]
	v_mfma_f32_16x16x32_bf16 v[68:71], v[192:195], v[184:187], v[68:71]
	v_mfma_f32_16x16x32_bf16 v[64:67], v[206:209], v[184:187], v[64:67]
	v_mov_b32_e32 v210, v130
	s_barrier
	ds_read_b128 v[156:159], v136 offset:49152
	ds_read_b128 v[160:163], v136 offset:50176
	ds_read_b128 v[164:167], v135 offset:49152
	ds_read_b128 v[168:171], v135 offset:50176
	ds_read_b128 v[172:175], v134 offset:49152
	ds_read_b128 v[176:179], v134 offset:50176
	ds_read_b128 v[180:183], v133 offset:49152
	ds_read_b128 v[184:187], v133 offset:50176
	v_mov_b32_e32 v211, v197
	s_mov_b32 m0, s9
	s_add_u32 s98, s28, s70
	s_addc_u32 s99, s29, s71
	global_load_lds_dwordx4 v128, s[98:99]
	s_mov_b32 m0, s33
	s_nop 0
	global_load_lds_dwordx4 v130, s[98:99]
	s_barrier
	s_waitcnt lgkmcnt(7)
	v_mfma_f32_16x16x32_bf16 v[60:63], v[140:143], v[156:159], v[60:63]
	v_mfma_f32_16x16x32_bf16 v[56:59], v[148:151], v[156:159], v[56:59]
	s_waitcnt lgkmcnt(5)
	v_mfma_f32_16x16x32_bf16 v[52:55], v[140:143], v[164:167], v[52:55]
	v_mfma_f32_16x16x32_bf16 v[48:51], v[148:151], v[164:167], v[48:51]
	s_waitcnt lgkmcnt(3)
	v_mfma_f32_16x16x32_bf16 v[44:47], v[140:143], v[172:175], v[44:47]
	v_mfma_f32_16x16x32_bf16 v[40:43], v[148:151], v[172:175], v[40:43]
	s_waitcnt lgkmcnt(1)
	v_mfma_f32_16x16x32_bf16 v[36:39], v[140:143], v[180:183], v[36:39]
	v_mfma_f32_16x16x32_bf16 v[32:35], v[148:151], v[180:183], v[32:35]
	v_mfma_f32_16x16x32_bf16 v[60:63], v[144:147], v[160:163], v[60:63]
	v_mfma_f32_16x16x32_bf16 v[56:59], v[152:155], v[160:163], v[56:59]
	v_mfma_f32_16x16x32_bf16 v[52:55], v[144:147], v[168:171], v[52:55]
	v_mfma_f32_16x16x32_bf16 v[48:51], v[152:155], v[168:171], v[48:51]
	v_mfma_f32_16x16x32_bf16 v[44:47], v[144:147], v[176:179], v[44:47]
	v_mfma_f32_16x16x32_bf16 v[40:43], v[152:155], v[176:179], v[40:43]
	s_waitcnt lgkmcnt(0)
	v_mfma_f32_16x16x32_bf16 v[36:39], v[144:147], v[184:187], v[36:39]
	v_mfma_f32_16x16x32_bf16 v[32:35], v[152:155], v[184:187], v[32:35]
	s_barrier
	v_mov_b32_e32 v196, v128
	s_mov_b32 m0, s65
	s_add_u32 s98, s58, s72
	s_addc_u32 s99, s59, s73
	global_load_lds_dwordx4 v128, s[98:99]
	s_mov_b32 m0, s66
	s_nop 0
	global_load_lds_dwordx4 v130, s[98:99]
	s_waitcnt vmcnt(6)
	s_barrier
	v_mfma_f32_16x16x32_bf16 v[28:31], v[188:191], v[156:159], v[28:31]
	v_mfma_f32_16x16x32_bf16 v[24:27], v[202:205], v[156:159], v[24:27]
	v_mfma_f32_16x16x32_bf16 v[20:23], v[188:191], v[164:167], v[20:23]
	v_mfma_f32_16x16x32_bf16 v[16:19], v[202:205], v[164:167], v[16:19]
	v_mfma_f32_16x16x32_bf16 v[12:15], v[188:191], v[172:175], v[12:15]
	v_mfma_f32_16x16x32_bf16 v[8:11], v[202:205], v[172:175], v[8:11]
	v_mfma_f32_16x16x32_bf16 v[4:7], v[188:191], v[180:183], v[4:7]
	v_mfma_f32_16x16x32_bf16 v[0:3], v[202:205], v[180:183], v[0:3]
	v_mfma_f32_16x16x32_bf16 v[28:31], v[192:195], v[160:163], v[28:31]
	v_mfma_f32_16x16x32_bf16 v[24:27], v[206:209], v[160:163], v[24:27]
	v_mfma_f32_16x16x32_bf16 v[20:23], v[192:195], v[168:171], v[20:23]
	v_mfma_f32_16x16x32_bf16 v[16:19], v[206:209], v[168:171], v[16:19]
	v_mfma_f32_16x16x32_bf16 v[12:15], v[192:195], v[176:179], v[12:15]
	v_mfma_f32_16x16x32_bf16 v[8:11], v[206:209], v[176:179], v[8:11]
	v_mfma_f32_16x16x32_bf16 v[4:7], v[192:195], v[184:187], v[4:7]
	v_mfma_f32_16x16x32_bf16 v[0:3], v[206:209], v[184:187], v[0:3]
	s_add_i32 s38, s38, 2
	s_add_u32 s56, s56, 0x100
	s_addc_u32 s57, s57, 0
	s_cmp_lt_u32 s38, 28
	s_barrier
	s_cbranch_scc1 .LBB0_192
	s_lshl_b64 s[4:5], s[10:11], 12
	v_readlane_b32 s10, v254, 12
	v_readlane_b32 s11, v254, 13
	s_add_u32 s4, s10, s4
	s_addc_u32 s5, s11, s5
	ds_read_b128 v[140:143], v129
	ds_read_b128 v[144:147], v129 offset:1024
	ds_read_b128 v[148:151], v129 offset:2048
	ds_read_b128 v[152:155], v129 offset:3072
	ds_read_b128 v[156:159], v136
	ds_read_b128 v[160:163], v136 offset:1024
	ds_read_b128 v[164:167], v135
	ds_read_b128 v[168:171], v135 offset:1024
	ds_read_b128 v[172:175], v134
	ds_read_b128 v[176:179], v134 offset:1024
	ds_read_b128 v[180:183], v133
	ds_read_b128 v[184:187], v133 offset:1024
	v_mov_b32_e32 v129, v197
	v_lshl_add_u64 v[128:129], s[4:5], 0, v[128:129]
	s_mov_b64 s[10:11], 0xf80
	s_mov_b32 m0, s40
	v_lshl_add_u64 v[128:129], v[128:129], 0, s[10:11]
	v_mov_b32_e32 v131, v197
	global_load_lds_dwordx4 v[128:129], off
	v_lshl_add_u64 v[128:129], s[4:5], 0, v[130:131]
	v_lshl_add_u64 v[128:129], v[128:129], 0, s[10:11]
	s_mov_b32 m0, s39
	s_nop 0
	global_load_lds_dwordx4 v[128:129], off
	s_barrier
	s_waitcnt lgkmcnt(0)
	s_setprio 1
	s_waitcnt lgkmcnt(0)
	v_mfma_f32_16x16x32_bf16 v[124:127], v[140:143], v[156:159], v[124:127]
	v_mfma_f32_16x16x32_bf16 v[116:119], v[140:143], v[164:167], v[116:119]
	v_mfma_f32_16x16x32_bf16 v[112:115], v[148:151], v[164:167], v[112:115]
	v_mfma_f32_16x16x32_bf16 v[108:111], v[140:143], v[172:175], v[108:111]
	v_mfma_f32_16x16x32_bf16 v[104:107], v[148:151], v[172:175], v[104:107]
	v_mfma_f32_16x16x32_bf16 v[100:103], v[140:143], v[180:183], v[100:103]
	v_mfma_f32_16x16x32_bf16 v[96:99], v[148:151], v[180:183], v[96:99]
	v_mfma_f32_16x16x32_bf16 v[124:127], v[144:147], v[160:163], v[124:127]
	v_mfma_f32_16x16x32_bf16 v[120:123], v[148:151], v[156:159], v[120:123]
	v_mfma_f32_16x16x32_bf16 v[116:119], v[144:147], v[168:171], v[116:119]
	v_mfma_f32_16x16x32_bf16 v[112:115], v[152:155], v[168:171], v[112:115]
	v_mfma_f32_16x16x32_bf16 v[108:111], v[144:147], v[176:179], v[108:111]
	v_mfma_f32_16x16x32_bf16 v[104:107], v[152:155], v[176:179], v[104:107]
	v_mfma_f32_16x16x32_bf16 v[100:103], v[144:147], v[184:187], v[100:103]
	v_mfma_f32_16x16x32_bf16 v[96:99], v[152:155], v[184:187], v[96:99]
	v_mfma_f32_16x16x32_bf16 v[128:131], v[152:155], v[160:163], v[120:123]
	s_setprio 0
	s_barrier
	s_nop 0
	ds_read_b128 v[120:123], v139
	ds_read_b128 v[188:191], v139 offset:1024
	ds_read_b128 v[192:195], v139 offset:2048
	ds_read_b128 v[202:205], v139 offset:3072
	s_barrier
	s_waitcnt lgkmcnt(0)
	s_setprio 1
	s_waitcnt lgkmcnt(0)
	v_mfma_f32_16x16x32_bf16 v[76:79], v[120:123], v[172:175], v[76:79]
	v_mfma_f32_16x16x32_bf16 v[68:71], v[120:123], v[180:183], v[68:71]
	v_mfma_f32_16x16x32_bf16 v[64:67], v[192:195], v[180:183], v[64:67]
	v_mfma_f32_16x16x32_bf16 v[92:95], v[120:123], v[156:159], v[92:95]
	v_mfma_f32_16x16x32_bf16 v[88:91], v[192:195], v[156:159], v[88:91]
	v_mfma_f32_16x16x32_bf16 v[84:87], v[120:123], v[164:167], v[84:87]
	v_mfma_f32_16x16x32_bf16 v[80:83], v[192:195], v[164:167], v[80:83]
	v_mfma_f32_16x16x32_bf16 v[76:79], v[188:191], v[176:179], v[76:79]
	v_mfma_f32_16x16x32_bf16 v[72:75], v[192:195], v[172:175], v[72:75]
	v_mfma_f32_16x16x32_bf16 v[68:71], v[188:191], v[184:187], v[68:71]
	v_mfma_f32_16x16x32_bf16 v[64:67], v[202:205], v[184:187], v[64:67]
	v_mfma_f32_16x16x32_bf16 v[206:209], v[188:191], v[160:163], v[92:95]
	v_mfma_f32_16x16x32_bf16 v[156:159], v[202:205], v[160:163], v[88:91]
	v_mfma_f32_16x16x32_bf16 v[160:163], v[188:191], v[168:171], v[84:87]
	v_mfma_f32_16x16x32_bf16 v[164:167], v[202:205], v[168:171], v[80:83]
	v_mfma_f32_16x16x32_bf16 v[168:171], v[202:205], v[176:179], v[72:75]
	s_setprio 0
	s_barrier
	s_nop 0
	ds_read_b128 v[72:75], v136 offset:16384
	ds_read_b128 v[80:83], v136 offset:17408
	ds_read_b128 v[84:87], v135 offset:16384
	ds_read_b128 v[88:91], v135 offset:17408
	ds_read_b128 v[92:95], v134 offset:16384
	ds_read_b128 v[172:175], v134 offset:17408
	ds_read_b128 v[176:179], v133 offset:16384
	ds_read_b128 v[180:183], v133 offset:17408
	s_waitcnt vmcnt(4)
	s_barrier
	s_waitcnt lgkmcnt(0)
	s_setprio 1
	s_waitcnt lgkmcnt(0)
	v_mfma_f32_16x16x32_bf16 v[60:63], v[140:143], v[72:75], v[60:63]
	v_mfma_f32_16x16x32_bf16 v[52:55], v[140:143], v[84:87], v[52:55]
	v_mfma_f32_16x16x32_bf16 v[48:51], v[148:151], v[84:87], v[48:51]
	v_mfma_f32_16x16x32_bf16 v[44:47], v[140:143], v[92:95], v[44:47]
	v_mfma_f32_16x16x32_bf16 v[40:43], v[148:151], v[92:95], v[40:43]
	v_mfma_f32_16x16x32_bf16 v[36:39], v[140:143], v[176:179], v[36:39]
	v_mfma_f32_16x16x32_bf16 v[32:35], v[148:151], v[176:179], v[32:35]
	v_mfma_f32_16x16x32_bf16 v[60:63], v[144:147], v[80:83], v[60:63]
	v_mfma_f32_16x16x32_bf16 v[56:59], v[148:151], v[72:75], v[56:59]
	v_mfma_f32_16x16x32_bf16 v[52:55], v[144:147], v[88:91], v[52:55]
	v_mfma_f32_16x16x32_bf16 v[48:51], v[152:155], v[88:91], v[48:51]
	v_mfma_f32_16x16x32_bf16 v[44:47], v[144:147], v[172:175], v[44:47]
	v_mfma_f32_16x16x32_bf16 v[40:43], v[152:155], v[172:175], v[40:43]
	v_mfma_f32_16x16x32_bf16 v[36:39], v[144:147], v[180:183], v[36:39]
	v_mfma_f32_16x16x32_bf16 v[32:35], v[152:155], v[180:183], v[32:35]
	v_mfma_f32_16x16x32_bf16 v[184:187], v[152:155], v[80:83], v[56:59]
	s_setprio 0
	s_setprio 1
	v_mfma_f32_16x16x32_bf16 v[12:15], v[120:123], v[92:95], v[12:15]
	v_mfma_f32_16x16x32_bf16 v[4:7], v[120:123], v[176:179], v[4:7]
	v_mfma_f32_16x16x32_bf16 v[0:3], v[192:195], v[176:179], v[0:3]
	v_mfma_f32_16x16x32_bf16 v[28:31], v[120:123], v[72:75], v[28:31]
	v_mfma_f32_16x16x32_bf16 v[24:27], v[192:195], v[72:75], v[24:27]
	v_mfma_f32_16x16x32_bf16 v[20:23], v[120:123], v[84:87], v[20:23]
	v_mfma_f32_16x16x32_bf16 v[16:19], v[192:195], v[84:87], v[16:19]
	v_mfma_f32_16x16x32_bf16 v[12:15], v[188:191], v[172:175], v[12:15]
	v_mfma_f32_16x16x32_bf16 v[8:11], v[192:195], v[92:95], v[8:11]
	v_mfma_f32_16x16x32_bf16 v[4:7], v[188:191], v[180:183], v[4:7]
	v_mfma_f32_16x16x32_bf16 v[0:3], v[202:205], v[180:183], v[0:3]
	v_mfma_f32_16x16x32_bf16 v[140:143], v[188:191], v[80:83], v[28:31]
	v_mfma_f32_16x16x32_bf16 v[144:147], v[202:205], v[80:83], v[24:27]
	v_mfma_f32_16x16x32_bf16 v[148:151], v[188:191], v[88:91], v[20:23]
	v_mfma_f32_16x16x32_bf16 v[152:155], v[202:205], v[88:91], v[16:19]
	v_mfma_f32_16x16x32_bf16 v[172:175], v[202:205], v[172:175], v[8:11]
	s_setprio 0
	s_barrier
	s_nop 0
	ds_read_b128 v[8:11], v138
	ds_read_b128 v[16:19], v138 offset:1024
	ds_read_b128 v[176:179], v138 offset:2048
	ds_read_b128 v[180:183], v138 offset:3072
	ds_read_b128 v[20:23], v136 offset:32768
	ds_read_b128 v[24:27], v136 offset:33792
	ds_read_b128 v[28:31], v135 offset:32768
	ds_read_b128 v[56:59], v135 offset:33792
	ds_read_b128 v[188:191], v134 offset:32768
	ds_read_b128 v[192:195], v134 offset:33792
	ds_read_b128 v[202:205], v133 offset:32768
	ds_read_b128 v[210:213], v133 offset:33792
	s_waitcnt vmcnt(2)
	s_barrier
	s_waitcnt lgkmcnt(0)
	s_setprio 1
	s_waitcnt lgkmcnt(0)
	v_mfma_f32_16x16x32_bf16 v[72:75], v[8:11], v[20:23], v[124:127]
	v_mfma_f32_16x16x32_bf16 v[120:123], v[16:19], v[24:27], v[72:75]
	v_mfma_f32_16x16x32_bf16 v[72:75], v[176:179], v[20:23], v[128:131]
	v_mfma_f32_16x16x32_bf16 v[124:127], v[180:183], v[24:27], v[72:75]
	v_mfma_f32_16x16x32_bf16 v[72:75], v[8:11], v[28:31], v[116:119]
	v_mfma_f32_16x16x32_bf16 v[116:119], v[16:19], v[56:59], v[72:75]
	v_mfma_f32_16x16x32_bf16 v[72:75], v[176:179], v[28:31], v[112:115]
	v_mfma_f32_16x16x32_bf16 v[112:115], v[180:183], v[56:59], v[72:75]
	v_mfma_f32_16x16x32_bf16 v[72:75], v[8:11], v[188:191], v[108:111]
	v_mfma_f32_16x16x32_bf16 v[88:91], v[16:19], v[192:195], v[72:75]
	v_mfma_f32_16x16x32_bf16 v[72:75], v[176:179], v[188:191], v[104:107]
	v_mfma_f32_16x16x32_bf16 v[92:95], v[180:183], v[192:195], v[72:75]
	v_mfma_f32_16x16x32_bf16 v[72:75], v[8:11], v[202:205], v[100:103]
	v_mfma_f32_16x16x32_bf16 v[84:87], v[16:19], v[210:213], v[72:75]
	v_mfma_f32_16x16x32_bf16 v[72:75], v[176:179], v[202:205], v[96:99]
	v_mfma_f32_16x16x32_bf16 v[80:83], v[180:183], v[210:213], v[72:75]
	s_setprio 0
	s_barrier
	ds_read_b128 v[128:131], v137
	ds_read_b128 v[214:217], v137 offset:1024
	ds_read_b128 v[218:221], v137 offset:2048
	ds_read_b128 v[222:225], v137 offset:3072
	s_waitcnt vmcnt(0)
	s_barrier
	s_waitcnt lgkmcnt(0)
	s_setprio 1
	s_waitcnt lgkmcnt(0)
	v_mfma_f32_16x16x32_bf16 v[72:75], v[128:131], v[20:23], v[206:209]
	v_mfma_f32_16x16x32_bf16 v[20:23], v[218:221], v[20:23], v[156:159]
	v_mfma_f32_16x16x32_bf16 v[108:111], v[222:225], v[24:27], v[20:23]
	v_mfma_f32_16x16x32_bf16 v[20:23], v[128:131], v[28:31], v[160:163]
	v_mfma_f32_16x16x32_bf16 v[100:103], v[214:217], v[56:59], v[20:23]
	v_mfma_f32_16x16x32_bf16 v[20:23], v[218:221], v[28:31], v[164:167]
	v_mfma_f32_16x16x32_bf16 v[96:99], v[222:225], v[56:59], v[20:23]
	v_mfma_f32_16x16x32_bf16 v[20:23], v[128:131], v[188:191], v[76:79]
	v_mfma_f32_16x16x32_bf16 v[104:107], v[214:217], v[24:27], v[72:75]
	v_mfma_f32_16x16x32_bf16 v[72:75], v[214:217], v[192:195], v[20:23]
	v_mfma_f32_16x16x32_bf16 v[20:23], v[218:221], v[188:191], v[168:171]
	v_mfma_f32_16x16x32_bf16 v[76:79], v[222:225], v[192:195], v[20:23]
	v_mfma_f32_16x16x32_bf16 v[20:23], v[128:131], v[202:205], v[68:71]
	v_mfma_f32_16x16x32_bf16 v[68:71], v[214:217], v[210:213], v[20:23]
	v_mfma_f32_16x16x32_bf16 v[20:23], v[218:221], v[202:205], v[64:67]
	v_mfma_f32_16x16x32_bf16 v[64:67], v[222:225], v[210:213], v[20:23]
	s_setprio 0
	s_barrier
	ds_read_b128 v[156:159], v136 offset:49152
	ds_read_b128 v[136:139], v136 offset:50176
	ds_read_b128 v[160:163], v135 offset:49152
	ds_read_b128 v[164:167], v135 offset:50176
	ds_read_b128 v[168:171], v134 offset:49152
	ds_read_b128 v[188:191], v134 offset:50176
	ds_read_b128 v[192:195], v133 offset:49152
	ds_read_b128 v[202:205], v133 offset:50176
	s_barrier
	s_waitcnt lgkmcnt(0)
	s_setprio 1
	s_waitcnt lgkmcnt(0)
	v_mfma_f32_16x16x32_bf16 v[20:23], v[8:11], v[156:159], v[60:63]
	v_mfma_f32_16x16x32_bf16 v[56:59], v[16:19], v[136:139], v[20:23]
	v_mfma_f32_16x16x32_bf16 v[20:23], v[176:179], v[156:159], v[184:187]
	v_mfma_f32_16x16x32_bf16 v[60:63], v[180:183], v[136:139], v[20:23]
	v_mfma_f32_16x16x32_bf16 v[20:23], v[8:11], v[160:163], v[52:55]
	v_mfma_f32_16x16x32_bf16 v[52:55], v[16:19], v[164:167], v[20:23]
	v_mfma_f32_16x16x32_bf16 v[20:23], v[176:179], v[160:163], v[48:51]
	v_mfma_f32_16x16x32_bf16 v[48:51], v[180:183], v[164:167], v[20:23]
	v_mfma_f32_16x16x32_bf16 v[20:23], v[8:11], v[168:171], v[44:47]
	v_mfma_f32_16x16x32_bf16 v[24:27], v[16:19], v[188:191], v[20:23]
	v_mfma_f32_16x16x32_bf16 v[20:23], v[176:179], v[168:171], v[40:43]
	v_mfma_f32_16x16x32_bf16 v[8:11], v[8:11], v[192:195], v[36:39]
	v_mfma_f32_16x16x32_bf16 v[28:31], v[180:183], v[188:191], v[20:23]
	v_mfma_f32_16x16x32_bf16 v[20:23], v[16:19], v[202:205], v[8:11]
	v_mfma_f32_16x16x32_bf16 v[8:11], v[176:179], v[192:195], v[32:35]
	v_mfma_f32_16x16x32_bf16 v[16:19], v[180:183], v[202:205], v[8:11]
	s_setprio 0
	s_setprio 1
	v_mfma_f32_16x16x32_bf16 v[8:11], v[128:131], v[156:159], v[140:143]
	v_mfma_f32_16x16x32_bf16 v[40:43], v[214:217], v[136:139], v[8:11]
	v_mfma_f32_16x16x32_bf16 v[8:11], v[218:221], v[156:159], v[144:147]
	v_mfma_f32_16x16x32_bf16 v[44:47], v[222:225], v[136:139], v[8:11]
	v_mfma_f32_16x16x32_bf16 v[8:11], v[128:131], v[160:163], v[148:151]
	v_mfma_f32_16x16x32_bf16 v[36:39], v[214:217], v[164:167], v[8:11]
	v_mfma_f32_16x16x32_bf16 v[8:11], v[218:221], v[160:163], v[152:155]
	v_mfma_f32_16x16x32_bf16 v[32:35], v[222:225], v[164:167], v[8:11]
	v_mfma_f32_16x16x32_bf16 v[8:11], v[128:131], v[168:171], v[12:15]
	v_mfma_f32_16x16x32_bf16 v[12:15], v[218:221], v[168:171], v[172:175]
	v_mfma_f32_16x16x32_bf16 v[4:7], v[128:131], v[192:195], v[4:7]
	v_mfma_f32_16x16x32_bf16 v[0:3], v[218:221], v[192:195], v[0:3]
	v_mfma_f32_16x16x32_bf16 v[8:11], v[214:217], v[188:191], v[8:11]
	v_mfma_f32_16x16x32_bf16 v[12:15], v[222:225], v[188:191], v[12:15]
	v_mfma_f32_16x16x32_bf16 v[4:7], v[214:217], v[202:205], v[4:7]
	v_mfma_f32_16x16x32_bf16 v[0:3], v[222:225], v[202:205], v[0:3]
	s_setprio 0
	s_movk_i32 s4, 0x100
	v_cmp_gt_u32_e32 vcc, s4, v132
	s_barrier
	s_and_saveexec_b64 s[4:5], vcc
	s_cbranch_execz .LBB0_195
	s_barrier

.LBB0_255:
	s_add_u32 s28, s60, s56
	s_addc_u32 s29, s61, s57
	s_add_i32 s40, s53, 0xc000
	s_mov_b32 m0, s40
	s_add_i32 s39, s53, 0xe000
	s_add_u32 s98, s28, s44
	s_addc_u32 s99, s29, s45
	global_load_lds_dwordx4 v128, s[98:99]
	s_mov_b32 m0, s39
	s_nop 0
	global_load_lds_dwordx4 v130, s[98:99]
	ds_read_b128 v[140:143], v129
	ds_read_b128 v[144:147], v129 offset:1024
	ds_read_b128 v[148:151], v129 offset:2048
	ds_read_b128 v[152:155], v129 offset:3072
	ds_read_b128 v[156:159], v136
	ds_read_b128 v[160:163], v136 offset:1024
	ds_read_b128 v[164:167], v135
	ds_read_b128 v[168:171], v135 offset:1024
	ds_read_b128 v[172:175], v134
	ds_read_b128 v[176:179], v134 offset:1024
	ds_read_b128 v[180:183], v133
	ds_read_b128 v[184:187], v133 offset:1024
	s_waitcnt lgkmcnt(8)
	s_barrier
	s_waitcnt lgkmcnt(7)
	v_mfma_f32_16x16x32_bf16 v[124:127], v[140:143], v[156:159], v[124:127]
	v_mfma_f32_16x16x32_bf16 v[120:123], v[148:151], v[156:159], v[120:123]
	s_waitcnt lgkmcnt(5)
	v_mfma_f32_16x16x32_bf16 v[116:119], v[140:143], v[164:167], v[116:119]
	v_mfma_f32_16x16x32_bf16 v[112:115], v[148:151], v[164:167], v[112:115]
	s_waitcnt lgkmcnt(3)
	v_mfma_f32_16x16x32_bf16 v[108:111], v[140:143], v[172:175], v[108:111]
	v_mfma_f32_16x16x32_bf16 v[104:107], v[148:151], v[172:175], v[104:107]
	s_waitcnt lgkmcnt(1)
	v_mfma_f32_16x16x32_bf16 v[100:103], v[140:143], v[180:183], v[100:103]
	v_mfma_f32_16x16x32_bf16 v[96:99], v[148:151], v[180:183], v[96:99]
	v_mfma_f32_16x16x32_bf16 v[124:127], v[144:147], v[160:163], v[124:127]
	v_mfma_f32_16x16x32_bf16 v[120:123], v[152:155], v[160:163], v[120:123]
	v_mfma_f32_16x16x32_bf16 v[116:119], v[144:147], v[168:171], v[116:119]
	v_mfma_f32_16x16x32_bf16 v[112:115], v[152:155], v[168:171], v[112:115]
	v_mfma_f32_16x16x32_bf16 v[108:111], v[144:147], v[176:179], v[108:111]
	v_mfma_f32_16x16x32_bf16 v[104:107], v[152:155], v[176:179], v[104:107]
	s_waitcnt lgkmcnt(0)
	v_mfma_f32_16x16x32_bf16 v[100:103], v[144:147], v[184:187], v[100:103]
	v_mfma_f32_16x16x32_bf16 v[96:99], v[152:155], v[184:187], v[96:99]
	s_barrier
	s_add_u32 s62, s60, s36
	s_addc_u32 s63, s61, s37
	s_mov_b32 m0, s68
	s_add_u32 s98, s62, s46
	s_addc_u32 s99, s63, s47
	global_load_lds_dwordx4 v128, s[98:99]
	s_mov_b32 m0, s69
	s_nop 0
	global_load_lds_dwordx4 v130, s[98:99]
	ds_read_b128 v[188:191], v139
	ds_read_b128 v[192:195], v139 offset:1024
	ds_read_b128 v[202:205], v139 offset:2048
	ds_read_b128 v[206:209], v139 offset:3072
	s_barrier
	s_waitcnt lgkmcnt(3)
	v_mfma_f32_16x16x32_bf16 v[92:95], v[188:191], v[156:159], v[92:95]
	s_waitcnt lgkmcnt(1)
	v_mfma_f32_16x16x32_bf16 v[88:91], v[202:205], v[156:159], v[88:91]
	v_mfma_f32_16x16x32_bf16 v[84:87], v[188:191], v[164:167], v[84:87]
	v_mfma_f32_16x16x32_bf16 v[80:83], v[202:205], v[164:167], v[80:83]
	v_mfma_f32_16x16x32_bf16 v[76:79], v[188:191], v[172:175], v[76:79]
	v_mfma_f32_16x16x32_bf16 v[72:75], v[202:205], v[172:175], v[72:75]
	v_mfma_f32_16x16x32_bf16 v[68:71], v[188:191], v[180:183], v[68:71]
	v_mfma_f32_16x16x32_bf16 v[64:67], v[202:205], v[180:183], v[64:67]
	v_mfma_f32_16x16x32_bf16 v[92:95], v[192:195], v[160:163], v[92:95]
	s_waitcnt lgkmcnt(0)
	v_mfma_f32_16x16x32_bf16 v[88:91], v[206:209], v[160:163], v[88:91]
	v_mfma_f32_16x16x32_bf16 v[84:87], v[192:195], v[168:171], v[84:87]
	v_mfma_f32_16x16x32_bf16 v[80:83], v[206:209], v[168:171], v[80:83]
	v_mfma_f32_16x16x32_bf16 v[76:79], v[192:195], v[176:179], v[76:79]
	v_mfma_f32_16x16x32_bf16 v[72:75], v[206:209], v[176:179], v[72:75]
	v_mfma_f32_16x16x32_bf16 v[68:71], v[192:195], v[184:187], v[68:71]
	v_mfma_f32_16x16x32_bf16 v[64:67], v[206:209], v[184:187], v[64:67]
	s_barrier
	s_mov_b32 m0, s53
	s_add_u32 s98, s28, s48
	s_addc_u32 s99, s29, s49
	global_load_lds_dwordx4 v128, s[98:99]
	s_mov_b32 m0, s11
	s_nop 0
	global_load_lds_dwordx4 v130, s[98:99]
	ds_read_b128 v[156:159], v136 offset:16384
	ds_read_b128 v[160:163], v136 offset:17408
	ds_read_b128 v[164:167], v135 offset:16384
	ds_read_b128 v[168:171], v135 offset:17408
	ds_read_b128 v[172:175], v134 offset:16384
	ds_read_b128 v[176:179], v134 offset:17408
	ds_read_b128 v[180:183], v133 offset:16384
	ds_read_b128 v[184:187], v133 offset:17408
	s_barrier
	s_waitcnt lgkmcnt(7)
	v_mfma_f32_16x16x32_bf16 v[60:63], v[140:143], v[156:159], v[60:63]
	v_mfma_f32_16x16x32_bf16 v[56:59], v[148:151], v[156:159], v[56:59]
	s_waitcnt lgkmcnt(5)
	v_mfma_f32_16x16x32_bf16 v[52:55], v[140:143], v[164:167], v[52:55]
	v_mfma_f32_16x16x32_bf16 v[48:51], v[148:151], v[164:167], v[48:51]
	s_waitcnt lgkmcnt(3)
	v_mfma_f32_16x16x32_bf16 v[44:47], v[140:143], v[172:175], v[44:47]
	v_mfma_f32_16x16x32_bf16 v[40:43], v[148:151], v[172:175], v[40:43]
	s_waitcnt lgkmcnt(1)
	v_mfma_f32_16x16x32_bf16 v[36:39], v[140:143], v[180:183], v[36:39]
	v_mfma_f32_16x16x32_bf16 v[32:35], v[148:151], v[180:183], v[32:35]
	v_mfma_f32_16x16x32_bf16 v[60:63], v[144:147], v[160:163], v[60:63]
	v_mfma_f32_16x16x32_bf16 v[56:59], v[152:155], v[160:163], v[56:59]
	v_mfma_f32_16x16x32_bf16 v[52:55], v[144:147], v[168:171], v[52:55]
	v_mfma_f32_16x16x32_bf16 v[48:51], v[152:155], v[168:171], v[48:51]
	v_mfma_f32_16x16x32_bf16 v[44:47], v[144:147], v[176:179], v[44:47]
	v_mfma_f32_16x16x32_bf16 v[40:43], v[152:155], v[176:179], v[40:43]
	s_waitcnt lgkmcnt(0)
	v_mfma_f32_16x16x32_bf16 v[36:39], v[144:147], v[184:187], v[36:39]
	v_mfma_f32_16x16x32_bf16 v[32:35], v[152:155], v[184:187], v[32:35]
	s_barrier
	s_mov_b32 m0, s9
	s_add_u32 s98, s62, s50
	s_addc_u32 s99, s63, s51
	global_load_lds_dwordx4 v128, s[98:99]
	s_mov_b32 m0, s70
	s_nop 0
	global_load_lds_dwordx4 v130, s[98:99]
	s_waitcnt vmcnt(6)
	s_barrier
	v_mfma_f32_16x16x32_bf16 v[28:31], v[188:191], v[156:159], v[28:31]
	v_mfma_f32_16x16x32_bf16 v[24:27], v[202:205], v[156:159], v[24:27]
	v_mfma_f32_16x16x32_bf16 v[20:23], v[188:191], v[164:167], v[20:23]
	v_mfma_f32_16x16x32_bf16 v[16:19], v[202:205], v[164:167], v[16:19]
	v_mfma_f32_16x16x32_bf16 v[12:15], v[188:191], v[172:175], v[12:15]
	v_mfma_f32_16x16x32_bf16 v[8:11], v[202:205], v[172:175], v[8:11]
	v_mfma_f32_16x16x32_bf16 v[4:7], v[188:191], v[180:183], v[4:7]
	v_mfma_f32_16x16x32_bf16 v[0:3], v[202:205], v[180:183], v[0:3]
	v_mfma_f32_16x16x32_bf16 v[28:31], v[192:195], v[160:163], v[28:31]
	v_mfma_f32_16x16x32_bf16 v[24:27], v[206:209], v[160:163], v[24:27]
	v_mfma_f32_16x16x32_bf16 v[20:23], v[192:195], v[168:171], v[20:23]
	v_mfma_f32_16x16x32_bf16 v[16:19], v[206:209], v[168:171], v[16:19]
	v_mfma_f32_16x16x32_bf16 v[12:15], v[192:195], v[176:179], v[12:15]
	v_mfma_f32_16x16x32_bf16 v[8:11], v[206:209], v[176:179], v[8:11]
	v_mfma_f32_16x16x32_bf16 v[4:7], v[192:195], v[184:187], v[4:7]
	v_mfma_f32_16x16x32_bf16 v[0:3], v[206:209], v[184:187], v[0:3]
	s_barrier
	s_mov_b32 m0, s71
	s_add_u32 s98, s28, s74
	s_addc_u32 s99, s29, s75
	global_load_lds_dwordx4 v128, s[98:99]
	s_mov_b32 m0, s72
	s_nop 0
	global_load_lds_dwordx4 v130, s[98:99]
	ds_read_b128 v[140:143], v138
	ds_read_b128 v[144:147], v138 offset:1024
	ds_read_b128 v[148:151], v138 offset:2048
	ds_read_b128 v[152:155], v138 offset:3072
	ds_read_b128 v[156:159], v136 offset:32768
	ds_read_b128 v[160:163], v136 offset:33792
	ds_read_b128 v[164:167], v135 offset:32768
	ds_read_b128 v[168:171], v135 offset:33792
	ds_read_b128 v[172:175], v134 offset:32768
	ds_read_b128 v[176:179], v134 offset:33792
	ds_read_b128 v[180:183], v133 offset:32768
	ds_read_b128 v[184:187], v133 offset:33792
	s_waitcnt lgkmcnt(8)
	s_barrier
	s_waitcnt lgkmcnt(7)
	v_mfma_f32_16x16x32_bf16 v[124:127], v[140:143], v[156:159], v[124:127]
	v_mfma_f32_16x16x32_bf16 v[120:123], v[148:151], v[156:159], v[120:123]
	s_waitcnt lgkmcnt(5)
	v_mfma_f32_16x16x32_bf16 v[116:119], v[140:143], v[164:167], v[116:119]
	v_mfma_f32_16x16x32_bf16 v[112:115], v[148:151], v[164:167], v[112:115]
	s_waitcnt lgkmcnt(3)
	v_mfma_f32_16x16x32_bf16 v[108:111], v[140:143], v[172:175], v[108:111]
	v_mfma_f32_16x16x32_bf16 v[104:107], v[148:151], v[172:175], v[104:107]
	s_waitcnt lgkmcnt(1)
	v_mfma_f32_16x16x32_bf16 v[100:103], v[140:143], v[180:183], v[100:103]
	v_mfma_f32_16x16x32_bf16 v[96:99], v[148:151], v[180:183], v[96:99]
	v_mfma_f32_16x16x32_bf16 v[124:127], v[144:147], v[160:163], v[124:127]
	v_mfma_f32_16x16x32_bf16 v[120:123], v[152:155], v[160:163], v[120:123]
	v_mfma_f32_16x16x32_bf16 v[116:119], v[144:147], v[168:171], v[116:119]
	v_mfma_f32_16x16x32_bf16 v[112:115], v[152:155], v[168:171], v[112:115]
	v_mfma_f32_16x16x32_bf16 v[108:111], v[144:147], v[176:179], v[108:111]
	v_mfma_f32_16x16x32_bf16 v[104:107], v[152:155], v[176:179], v[104:107]
	s_waitcnt lgkmcnt(0)
	v_mfma_f32_16x16x32_bf16 v[100:103], v[144:147], v[184:187], v[100:103]
	v_mfma_f32_16x16x32_bf16 v[96:99], v[152:155], v[184:187], v[96:99]
	s_barrier
	s_mov_b32 m0, s66
	s_add_u32 s98, s62, s90
	s_addc_u32 s99, s63, s91
	global_load_lds_dwordx4 v128, s[98:99]
	s_mov_b32 m0, s64
	s_nop 0
	global_load_lds_dwordx4 v130, s[98:99]
	ds_read_b128 v[188:191], v137
	ds_read_b128 v[192:195], v137 offset:1024
	ds_read_b128 v[202:205], v137 offset:2048
	ds_read_b128 v[206:209], v137 offset:3072
	s_barrier
	s_waitcnt lgkmcnt(3)
	v_mfma_f32_16x16x32_bf16 v[92:95], v[188:191], v[156:159], v[92:95]
	s_waitcnt lgkmcnt(1)
	v_mfma_f32_16x16x32_bf16 v[88:91], v[202:205], v[156:159], v[88:91]
	v_mfma_f32_16x16x32_bf16 v[84:87], v[188:191], v[164:167], v[84:87]
	v_mfma_f32_16x16x32_bf16 v[80:83], v[202:205], v[164:167], v[80:83]
	v_mfma_f32_16x16x32_bf16 v[76:79], v[188:191], v[172:175], v[76:79]
	v_mfma_f32_16x16x32_bf16 v[72:75], v[202:205], v[172:175], v[72:75]
	v_mfma_f32_16x16x32_bf16 v[68:71], v[188:191], v[180:183], v[68:71]
	v_mfma_f32_16x16x32_bf16 v[64:67], v[202:205], v[180:183], v[64:67]
	v_mfma_f32_16x16x32_bf16 v[92:95], v[192:195], v[160:163], v[92:95]
	s_waitcnt lgkmcnt(0)
	v_mfma_f32_16x16x32_bf16 v[88:91], v[206:209], v[160:163], v[88:91]
	v_mfma_f32_16x16x32_bf16 v[84:87], v[192:195], v[168:171], v[84:87]
	v_mfma_f32_16x16x32_bf16 v[80:83], v[206:209], v[168:171], v[80:83]
	v_mfma_f32_16x16x32_bf16 v[76:79], v[192:195], v[176:179], v[76:79]
	v_mfma_f32_16x16x32_bf16 v[72:75], v[206:209], v[176:179], v[72:75]
	v_mfma_f32_16x16x32_bf16 v[68:71], v[192:195], v[184:187], v[68:71]
	v_mfma_f32_16x16x32_bf16 v[64:67], v[206:209], v[184:187], v[64:67]
	v_mov_b32_e32 v210, v130
	s_barrier
	ds_read_b128 v[156:159], v136 offset:49152
	ds_read_b128 v[160:163], v136 offset:50176
	ds_read_b128 v[164:167], v135 offset:49152
	ds_read_b128 v[168:171], v135 offset:50176
	ds_read_b128 v[172:175], v134 offset:49152
	ds_read_b128 v[176:179], v134 offset:50176
	ds_read_b128 v[180:183], v133 offset:49152
	ds_read_b128 v[184:187], v133 offset:50176
	v_mov_b32_e32 v211, v197
	s_mov_b32 m0, s65
	s_add_u32 s98, s28, s92
	s_addc_u32 s99, s29, s93
	global_load_lds_dwordx4 v128, s[98:99]
	s_mov_b32 m0, s67
	s_nop 0
	global_load_lds_dwordx4 v130, s[98:99]
	s_barrier
	s_waitcnt lgkmcnt(7)
	v_mfma_f32_16x16x32_bf16 v[60:63], v[140:143], v[156:159], v[60:63]
	v_mfma_f32_16x16x32_bf16 v[56:59], v[148:151], v[156:159], v[56:59]
	s_waitcnt lgkmcnt(5)
	v_mfma_f32_16x16x32_bf16 v[52:55], v[140:143], v[164:167], v[52:55]
	v_mfma_f32_16x16x32_bf16 v[48:51], v[148:151], v[164:167], v[48:51]
	s_waitcnt lgkmcnt(3)
	v_mfma_f32_16x16x32_bf16 v[44:47], v[140:143], v[172:175], v[44:47]
	v_mfma_f32_16x16x32_bf16 v[40:43], v[148:151], v[172:175], v[40:43]
	s_waitcnt lgkmcnt(1)
	v_mfma_f32_16x16x32_bf16 v[36:39], v[140:143], v[180:183], v[36:39]
	v_mfma_f32_16x16x32_bf16 v[32:35], v[148:151], v[180:183], v[32:35]
	v_mfma_f32_16x16x32_bf16 v[60:63], v[144:147], v[160:163], v[60:63]
	v_mfma_f32_16x16x32_bf16 v[56:59], v[152:155], v[160:163], v[56:59]
	v_mfma_f32_16x16x32_bf16 v[52:55], v[144:147], v[168:171], v[52:55]
	v_mfma_f32_16x16x32_bf16 v[48:51], v[152:155], v[168:171], v[48:51]
	v_mfma_f32_16x16x32_bf16 v[44:47], v[144:147], v[176:179], v[44:47]
	v_mfma_f32_16x16x32_bf16 v[40:43], v[152:155], v[176:179], v[40:43]
	s_waitcnt lgkmcnt(0)
	v_mfma_f32_16x16x32_bf16 v[36:39], v[144:147], v[184:187], v[36:39]
	v_mfma_f32_16x16x32_bf16 v[32:35], v[152:155], v[184:187], v[32:35]
	s_barrier
	v_mov_b32_e32 v196, v128
	s_mov_b32 m0, s33
	s_add_u32 s98, s62, s96
	s_addc_u32 s99, s63, s97
	global_load_lds_dwordx4 v128, s[98:99]
	s_mov_b32 m0, s73
	s_nop 0
	global_load_lds_dwordx4 v130, s[98:99]
	s_waitcnt vmcnt(6)
	s_barrier
	v_mfma_f32_16x16x32_bf16 v[28:31], v[188:191], v[156:159], v[28:31]
	v_mfma_f32_16x16x32_bf16 v[24:27], v[202:205], v[156:159], v[24:27]
	v_mfma_f32_16x16x32_bf16 v[20:23], v[188:191], v[164:167], v[20:23]
	v_mfma_f32_16x16x32_bf16 v[16:19], v[202:205], v[164:167], v[16:19]
	v_mfma_f32_16x16x32_bf16 v[12:15], v[188:191], v[172:175], v[12:15]
	v_mfma_f32_16x16x32_bf16 v[8:11], v[202:205], v[172:175], v[8:11]
	v_mfma_f32_16x16x32_bf16 v[4:7], v[188:191], v[180:183], v[4:7]
	v_mfma_f32_16x16x32_bf16 v[0:3], v[202:205], v[180:183], v[0:3]
	v_mfma_f32_16x16x32_bf16 v[28:31], v[192:195], v[160:163], v[28:31]
	v_mfma_f32_16x16x32_bf16 v[24:27], v[206:209], v[160:163], v[24:27]
	v_mfma_f32_16x16x32_bf16 v[20:23], v[192:195], v[168:171], v[20:23]
	v_mfma_f32_16x16x32_bf16 v[16:19], v[206:209], v[168:171], v[16:19]
	v_mfma_f32_16x16x32_bf16 v[12:15], v[192:195], v[176:179], v[12:15]
	v_mfma_f32_16x16x32_bf16 v[8:11], v[206:209], v[176:179], v[8:11]
	v_mfma_f32_16x16x32_bf16 v[4:7], v[192:195], v[184:187], v[4:7]
	v_mfma_f32_16x16x32_bf16 v[0:3], v[206:209], v[184:187], v[0:3]
	s_add_i32 s38, s38, 2
	s_add_u32 s60, s60, 0x100
	s_addc_u32 s61, s61, 0
	s_cmp_lt_u32 s38, 28
	s_barrier
	s_cbranch_scc1 .LBB0_255
	ds_read_b128 v[140:143], v129
	ds_read_b128 v[144:147], v129 offset:1024
	ds_read_b128 v[148:151], v129 offset:2048
	ds_read_b128 v[152:155], v129 offset:3072
	ds_read_b128 v[156:159], v136
	ds_read_b128 v[160:163], v136 offset:1024
	ds_read_b128 v[164:167], v135
	ds_read_b128 v[168:171], v135 offset:1024
	ds_read_b128 v[172:175], v134
	ds_read_b128 v[176:179], v134 offset:1024
	ds_read_b128 v[180:183], v133
	ds_read_b128 v[184:187], v133 offset:1024
	v_mov_b32_e32 v129, v197
	v_lshl_add_u64 v[128:129], s[58:59], 0, v[128:129]
	s_mov_b64 s[28:29], 0xf80
	s_mov_b32 m0, s40
	v_lshl_add_u64 v[128:129], v[128:129], 0, s[28:29]
	v_mov_b32_e32 v131, v197
	global_load_lds_dwordx4 v[128:129], off
	v_lshl_add_u64 v[128:129], s[58:59], 0, v[130:131]
	v_lshl_add_u64 v[128:129], v[128:129], 0, s[28:29]
	s_mov_b32 m0, s39
	s_nop 0
	global_load_lds_dwordx4 v[128:129], off
	s_barrier
	s_waitcnt lgkmcnt(0)
	s_setprio 1
	s_waitcnt lgkmcnt(0)
	v_mfma_f32_16x16x32_bf16 v[124:127], v[140:143], v[156:159], v[124:127]
	v_mfma_f32_16x16x32_bf16 v[120:123], v[148:151], v[156:159], v[120:123]
	v_mfma_f32_16x16x32_bf16 v[116:119], v[140:143], v[164:167], v[116:119]
	v_mfma_f32_16x16x32_bf16 v[112:115], v[148:151], v[164:167], v[112:115]
	v_mfma_f32_16x16x32_bf16 v[108:111], v[140:143], v[172:175], v[108:111]
	v_mfma_f32_16x16x32_bf16 v[100:103], v[140:143], v[180:183], v[100:103]
	v_mfma_f32_16x16x32_bf16 v[96:99], v[148:151], v[180:183], v[96:99]
	v_mfma_f32_16x16x32_bf16 v[124:127], v[144:147], v[160:163], v[124:127]
	v_mfma_f32_16x16x32_bf16 v[120:123], v[152:155], v[160:163], v[120:123]
	v_mfma_f32_16x16x32_bf16 v[116:119], v[144:147], v[168:171], v[116:119]
	v_mfma_f32_16x16x32_bf16 v[112:115], v[152:155], v[168:171], v[112:115]
	v_mfma_f32_16x16x32_bf16 v[108:111], v[144:147], v[176:179], v[108:111]
	v_mfma_f32_16x16x32_bf16 v[104:107], v[148:151], v[172:175], v[104:107]
	v_mfma_f32_16x16x32_bf16 v[100:103], v[144:147], v[184:187], v[100:103]
	v_mfma_f32_16x16x32_bf16 v[96:99], v[152:155], v[184:187], v[96:99]
	v_mfma_f32_16x16x32_bf16 v[128:131], v[152:155], v[176:179], v[104:107]
	s_setprio 0
	s_barrier
	s_nop 2
	ds_read_b128 v[104:107], v139
	ds_read_b128 v[188:191], v139 offset:1024
	ds_read_b128 v[192:195], v139 offset:2048
	ds_read_b128 v[202:205], v139 offset:3072
	s_barrier
	s_waitcnt lgkmcnt(0)
	s_setprio 1
	s_waitcnt lgkmcnt(0)
	v_mfma_f32_16x16x32_bf16 v[92:95], v[104:107], v[156:159], v[92:95]
	v_mfma_f32_16x16x32_bf16 v[84:87], v[104:107], v[164:167], v[84:87]
	v_mfma_f32_16x16x32_bf16 v[76:79], v[104:107], v[172:175], v[76:79]
	v_mfma_f32_16x16x32_bf16 v[68:71], v[104:107], v[180:183], v[68:71]
	v_mfma_f32_16x16x32_bf16 v[64:67], v[192:195], v[180:183], v[64:67]
	v_mfma_f32_16x16x32_bf16 v[92:95], v[188:191], v[160:163], v[92:95]
	v_mfma_f32_16x16x32_bf16 v[88:91], v[192:195], v[156:159], v[88:91]
	v_mfma_f32_16x16x32_bf16 v[84:87], v[188:191], v[168:171], v[84:87]
	v_mfma_f32_16x16x32_bf16 v[80:83], v[192:195], v[164:167], v[80:83]
	v_mfma_f32_16x16x32_bf16 v[76:79], v[188:191], v[176:179], v[76:79]
	v_mfma_f32_16x16x32_bf16 v[72:75], v[192:195], v[172:175], v[72:75]
	v_mfma_f32_16x16x32_bf16 v[68:71], v[188:191], v[184:187], v[68:71]
	v_mfma_f32_16x16x32_bf16 v[64:67], v[202:205], v[184:187], v[64:67]
	v_mfma_f32_16x16x32_bf16 v[156:159], v[202:205], v[160:163], v[88:91]
	v_mfma_f32_16x16x32_bf16 v[160:163], v[202:205], v[168:171], v[80:83]
	v_mfma_f32_16x16x32_bf16 v[164:167], v[202:205], v[176:179], v[72:75]
	s_setprio 0
	s_barrier
	s_nop 0
	ds_read_b128 v[72:75], v136 offset:16384
	ds_read_b128 v[80:83], v136 offset:17408
	ds_read_b128 v[88:91], v135 offset:16384
	ds_read_b128 v[168:171], v135 offset:17408
	ds_read_b128 v[172:175], v134 offset:16384
	ds_read_b128 v[176:179], v134 offset:17408
	ds_read_b128 v[180:183], v133 offset:16384
	ds_read_b128 v[184:187], v133 offset:17408
	s_waitcnt vmcnt(4)
	s_barrier
	s_waitcnt lgkmcnt(0)
	s_setprio 1
	s_waitcnt lgkmcnt(0)
	v_mfma_f32_16x16x32_bf16 v[60:63], v[140:143], v[72:75], v[60:63]
	v_mfma_f32_16x16x32_bf16 v[56:59], v[148:151], v[72:75], v[56:59]
	v_mfma_f32_16x16x32_bf16 v[48:51], v[148:151], v[88:91], v[48:51]
	v_mfma_f32_16x16x32_bf16 v[32:35], v[148:151], v[180:183], v[32:35]
	v_mfma_f32_16x16x32_bf16 v[60:63], v[144:147], v[80:83], v[60:63]
	v_mfma_f32_16x16x32_bf16 v[56:59], v[152:155], v[80:83], v[56:59]
	v_mfma_f32_16x16x32_bf16 v[52:55], v[140:143], v[88:91], v[52:55]
	v_mfma_f32_16x16x32_bf16 v[48:51], v[152:155], v[168:171], v[48:51]
	v_mfma_f32_16x16x32_bf16 v[44:47], v[140:143], v[172:175], v[44:47]
	v_mfma_f32_16x16x32_bf16 v[40:43], v[148:151], v[172:175], v[40:43]
	v_mfma_f32_16x16x32_bf16 v[36:39], v[140:143], v[180:183], v[36:39]
	v_mfma_f32_16x16x32_bf16 v[32:35], v[152:155], v[184:187], v[32:35]
	v_mfma_f32_16x16x32_bf16 v[206:209], v[144:147], v[168:171], v[52:55]
	v_mfma_f32_16x16x32_bf16 v[210:213], v[144:147], v[176:179], v[44:47]
	v_mfma_f32_16x16x32_bf16 v[214:217], v[152:155], v[176:179], v[40:43]
	v_mfma_f32_16x16x32_bf16 v[140:143], v[144:147], v[184:187], v[36:39]
	s_setprio 0
	s_setprio 1
	v_mfma_f32_16x16x32_bf16 v[24:27], v[192:195], v[72:75], v[24:27]
	v_mfma_f32_16x16x32_bf16 v[20:23], v[104:107], v[88:91], v[20:23]
	v_mfma_f32_16x16x32_bf16 v[28:31], v[104:107], v[72:75], v[28:31]
	v_mfma_f32_16x16x32_bf16 v[24:27], v[202:205], v[80:83], v[24:27]
	v_mfma_f32_16x16x32_bf16 v[20:23], v[188:191], v[168:171], v[20:23]
	v_mfma_f32_16x16x32_bf16 v[16:19], v[192:195], v[88:91], v[16:19]
	v_mfma_f32_16x16x32_bf16 v[12:15], v[104:107], v[172:175], v[12:15]
	v_mfma_f32_16x16x32_bf16 v[8:11], v[192:195], v[172:175], v[8:11]
	v_mfma_f32_16x16x32_bf16 v[4:7], v[104:107], v[180:183], v[4:7]
	v_mfma_f32_16x16x32_bf16 v[0:3], v[192:195], v[180:183], v[0:3]
	v_mfma_f32_16x16x32_bf16 v[144:147], v[188:191], v[80:83], v[28:31]
	v_mfma_f32_16x16x32_bf16 v[148:151], v[202:205], v[168:171], v[16:19]
	v_mfma_f32_16x16x32_bf16 v[152:155], v[188:191], v[176:179], v[12:15]
	v_mfma_f32_16x16x32_bf16 v[168:171], v[202:205], v[176:179], v[8:11]
	v_mfma_f32_16x16x32_bf16 v[172:175], v[188:191], v[184:187], v[4:7]
	v_mfma_f32_16x16x32_bf16 v[176:179], v[202:205], v[184:187], v[0:3]
	s_setprio 0
	s_barrier
	ds_read_b128 v[16:19], v138
	ds_read_b128 v[180:183], v138 offset:1024
	ds_read_b128 v[184:187], v138 offset:2048
	ds_read_b128 v[188:191], v138 offset:3072
	ds_read_b128 v[0:3], v136 offset:32768
	ds_read_b128 v[4:7], v136 offset:33792
	ds_read_b128 v[8:11], v135 offset:32768
	ds_read_b128 v[12:15], v135 offset:33792
	ds_read_b128 v[44:47], v134 offset:32768
	ds_read_b128 v[192:195], v134 offset:33792
	ds_read_b128 v[202:205], v133 offset:32768
	ds_read_b128 v[218:221], v133 offset:33792
	s_waitcnt vmcnt(2)
	s_barrier
	s_waitcnt lgkmcnt(0)
	s_setprio 1
	s_waitcnt lgkmcnt(0)
	v_mfma_f32_16x16x32_bf16 v[28:31], v[16:19], v[0:3], v[124:127]
	v_mfma_f32_16x16x32_bf16 v[52:55], v[180:183], v[4:7], v[28:31]
	v_mfma_f32_16x16x32_bf16 v[28:31], v[184:187], v[0:3], v[120:123]
	v_mfma_f32_16x16x32_bf16 v[104:107], v[188:191], v[4:7], v[28:31]
	v_mfma_f32_16x16x32_bf16 v[28:31], v[16:19], v[8:11], v[116:119]
	v_mfma_f32_16x16x32_bf16 v[72:75], v[180:183], v[12:15], v[28:31]
	v_mfma_f32_16x16x32_bf16 v[28:31], v[184:187], v[8:11], v[112:115]
	v_mfma_f32_16x16x32_bf16 v[116:119], v[188:191], v[12:15], v[28:31]
	v_mfma_f32_16x16x32_bf16 v[28:31], v[16:19], v[44:47], v[108:111]
	v_mfma_f32_16x16x32_bf16 v[80:83], v[180:183], v[192:195], v[28:31]
	v_mfma_f32_16x16x32_bf16 v[28:31], v[184:187], v[44:47], v[128:131]
	v_mfma_f32_16x16x32_bf16 v[108:111], v[188:191], v[192:195], v[28:31]
	v_mfma_f32_16x16x32_bf16 v[28:31], v[16:19], v[202:205], v[100:103]
	v_mfma_f32_16x16x32_bf16 v[88:91], v[180:183], v[218:221], v[28:31]
	v_mfma_f32_16x16x32_bf16 v[28:31], v[184:187], v[202:205], v[96:99]
	v_mfma_f32_16x16x32_bf16 v[96:99], v[188:191], v[218:221], v[28:31]
	s_setprio 0
	s_barrier
	ds_read_b128 v[128:131], v137
	ds_read_b128 v[222:225], v137 offset:1024
	ds_read_b128 v[228:231], v137 offset:2048
	ds_read_b128 v[232:235], v137 offset:3072
	s_waitcnt vmcnt(0)
	s_barrier
	s_waitcnt lgkmcnt(0)
	s_setprio 1
	s_waitcnt lgkmcnt(0)
	v_mfma_f32_16x16x32_bf16 v[28:31], v[128:131], v[0:3], v[92:95]
	v_mfma_f32_16x16x32_bf16 v[0:3], v[228:231], v[0:3], v[156:159]
	v_mfma_f32_16x16x32_bf16 v[28:31], v[222:225], v[4:7], v[28:31]
	v_mfma_f32_16x16x32_bf16 v[0:3], v[232:235], v[4:7], v[0:3]
	v_mfma_f32_16x16x32_bf16 v[4:7], v[128:131], v[8:11], v[84:87]
	v_mfma_f32_16x16x32_bf16 v[36:39], v[222:225], v[12:15], v[4:7]
	v_mfma_f32_16x16x32_bf16 v[4:7], v[228:231], v[8:11], v[160:163]
	v_mfma_f32_16x16x32_bf16 v[4:7], v[232:235], v[12:15], v[4:7]
	v_mfma_f32_16x16x32_bf16 v[8:11], v[128:131], v[44:47], v[76:79]
	v_mfma_f32_16x16x32_bf16 v[12:15], v[128:131], v[202:205], v[68:71]
	v_mfma_f32_16x16x32_bf16 v[40:43], v[222:225], v[192:195], v[8:11]
	v_mfma_f32_16x16x32_bf16 v[8:11], v[228:231], v[44:47], v[164:167]
	v_mfma_f32_16x16x32_bf16 v[44:47], v[222:225], v[218:221], v[12:15]
	v_mfma_f32_16x16x32_bf16 v[12:15], v[228:231], v[202:205], v[64:67]
	v_mfma_f32_16x16x32_bf16 v[8:11], v[232:235], v[192:195], v[8:11]
	v_mfma_f32_16x16x32_bf16 v[12:15], v[232:235], v[218:221], v[12:15]
	s_setprio 0
	s_barrier
	ds_read_b128 v[64:67], v136 offset:49152
	ds_read_b128 v[136:139], v136 offset:50176
	ds_read_b128 v[156:159], v135 offset:49152
	ds_read_b128 v[160:163], v135 offset:50176
	ds_read_b128 v[164:167], v134 offset:49152
	ds_read_b128 v[192:195], v134 offset:50176
	ds_read_b128 v[202:205], v133 offset:49152
	ds_read_b128 v[218:221], v133 offset:50176
	s_barrier
	s_waitcnt lgkmcnt(0)
	s_setprio 1
	s_waitcnt lgkmcnt(0)
	v_mfma_f32_16x16x32_bf16 v[56:59], v[184:187], v[64:67], v[56:59]
	v_mfma_f32_16x16x32_bf16 v[48:51], v[184:187], v[156:159], v[48:51]
	v_mfma_f32_16x16x32_bf16 v[60:63], v[16:19], v[64:67], v[60:63]
	v_mfma_f32_16x16x32_bf16 v[92:95], v[188:191], v[136:139], v[56:59]
	v_mfma_f32_16x16x32_bf16 v[56:59], v[16:19], v[156:159], v[206:209]
	v_mfma_f32_16x16x32_bf16 v[84:87], v[188:191], v[160:163], v[48:51]
	v_mfma_f32_16x16x32_bf16 v[48:51], v[16:19], v[164:167], v[210:213]
	v_mfma_f32_16x16x32_bf16 v[16:19], v[16:19], v[202:205], v[140:143]
	v_mfma_f32_16x16x32_bf16 v[120:123], v[180:183], v[192:195], v[48:51]
	v_mfma_f32_16x16x32_bf16 v[48:51], v[184:187], v[164:167], v[214:217]
	v_mfma_f32_16x16x32_bf16 v[124:127], v[180:183], v[218:221], v[16:19]
	v_mfma_f32_16x16x32_bf16 v[16:19], v[184:187], v[202:205], v[32:35]
	v_mfma_f32_16x16x32_bf16 v[100:103], v[180:183], v[136:139], v[60:63]
	v_mfma_f32_16x16x32_bf16 v[112:115], v[180:183], v[160:163], v[56:59]
	v_mfma_f32_16x16x32_bf16 v[76:79], v[188:191], v[192:195], v[48:51]
	v_mfma_f32_16x16x32_bf16 v[68:71], v[188:191], v[218:221], v[16:19]
	s_setprio 0
	s_setprio 1
	v_mfma_f32_16x16x32_bf16 v[16:19], v[128:131], v[64:67], v[144:147]
	v_mfma_f32_16x16x32_bf16 v[48:51], v[222:225], v[136:139], v[16:19]
	v_mfma_f32_16x16x32_bf16 v[16:19], v[228:231], v[64:67], v[24:27]
	v_mfma_f32_16x16x32_bf16 v[20:23], v[128:131], v[156:159], v[20:23]
	v_mfma_f32_16x16x32_bf16 v[24:27], v[128:131], v[164:167], v[152:155]
	v_mfma_f32_16x16x32_bf16 v[32:35], v[128:131], v[202:205], v[172:175]
	v_mfma_f32_16x16x32_bf16 v[56:59], v[222:225], v[160:163], v[20:23]
	v_mfma_f32_16x16x32_bf16 v[20:23], v[228:231], v[156:159], v[148:151]
	v_mfma_f32_16x16x32_bf16 v[60:63], v[222:225], v[192:195], v[24:27]
	v_mfma_f32_16x16x32_bf16 v[24:27], v[228:231], v[164:167], v[168:171]
	v_mfma_f32_16x16x32_bf16 v[64:67], v[222:225], v[218:221], v[32:35]
	v_mfma_f32_16x16x32_bf16 v[32:35], v[228:231], v[202:205], v[176:179]
	v_mfma_f32_16x16x32_bf16 v[16:19], v[232:235], v[136:139], v[16:19]
	v_mfma_f32_16x16x32_bf16 v[20:23], v[232:235], v[160:163], v[20:23]
	v_mfma_f32_16x16x32_bf16 v[24:27], v[232:235], v[192:195], v[24:27]
	v_mfma_f32_16x16x32_bf16 v[32:35], v[232:235], v[218:221], v[32:35]
	s_setprio 0
	s_movk_i32 s9, 0x100
	v_cmp_gt_u32_e32 vcc, s9, v132
	s_barrier
	s_and_saveexec_b64 s[28:29], vcc
	s_cbranch_execz .LBB0_212
	s_barrier
	s_branch .LBB0_212

.LBB0_314:
	s_add_u32 s8, s37, vcc_lo
	s_addc_u32 s9, s38, vcc_hi
	s_add_i32 s40, s34, 0xc000
	s_mov_b32 m0, s40
	s_add_i32 s41, s34, 0xe000
	s_add_u32 s98, s8, s94
	s_addc_u32 s99, s9, s95
	global_load_lds_dwordx4 v160, s[98:99]
	s_mov_b32 m0, s41
	s_nop 0
	global_load_lds_dwordx4 v161, s[98:99]
	ds_read_b128 v[172:175], v170
	ds_read_b128 v[176:179], v170 offset:1024
	ds_read_b128 v[180:183], v170 offset:2048
	ds_read_b128 v[184:187], v170 offset:3072
	ds_read_b128 v[188:191], v166
	ds_read_b128 v[192:195], v166 offset:1024
	ds_read_b128 v[202:205], v165
	ds_read_b128 v[206:209], v165 offset:1024
	ds_read_b128 v[210:213], v163
	ds_read_b128 v[214:217], v163 offset:1024
	ds_read_b128 v[218:221], v162
	ds_read_b128 v[236:239], v162 offset:1024
	s_waitcnt lgkmcnt(8)
	s_barrier
	s_waitcnt lgkmcnt(7)
	v_mfma_f32_16x16x32_bf16 v[44:47], v[172:175], v[188:191], v[44:47]
	v_mfma_f32_16x16x32_bf16 v[40:43], v[180:183], v[188:191], v[40:43]
	s_waitcnt lgkmcnt(5)
	v_mfma_f32_16x16x32_bf16 v[60:63], v[172:175], v[202:205], v[60:63]
	v_mfma_f32_16x16x32_bf16 v[56:59], v[180:183], v[202:205], v[56:59]
	s_waitcnt lgkmcnt(3)
	v_mfma_f32_16x16x32_bf16 v[76:79], v[172:175], v[210:213], v[76:79]
	v_mfma_f32_16x16x32_bf16 v[72:75], v[180:183], v[210:213], v[72:75]
	s_waitcnt lgkmcnt(1)
	v_mfma_f32_16x16x32_bf16 v[92:95], v[172:175], v[218:221], v[92:95]
	v_mfma_f32_16x16x32_bf16 v[88:91], v[180:183], v[218:221], v[88:91]
	v_mfma_f32_16x16x32_bf16 v[44:47], v[176:179], v[192:195], v[44:47]
	v_mfma_f32_16x16x32_bf16 v[40:43], v[184:187], v[192:195], v[40:43]
	v_mfma_f32_16x16x32_bf16 v[60:63], v[176:179], v[206:209], v[60:63]
	v_mfma_f32_16x16x32_bf16 v[56:59], v[184:187], v[206:209], v[56:59]
	v_mfma_f32_16x16x32_bf16 v[76:79], v[176:179], v[214:217], v[76:79]
	v_mfma_f32_16x16x32_bf16 v[72:75], v[184:187], v[214:217], v[72:75]
	s_waitcnt lgkmcnt(0)
	v_mfma_f32_16x16x32_bf16 v[92:95], v[176:179], v[236:239], v[92:95]
	v_mfma_f32_16x16x32_bf16 v[88:91], v[184:187], v[236:239], v[88:91]
	s_barrier
	s_add_i32 s39, s39, 2
	s_add_u32 s28, s6, vcc_lo
	s_addc_u32 s29, s7, vcc_hi
	s_mov_b32 m0, s59
	s_add_u32 s98, s28, s0
	s_addc_u32 s99, s29, s1
	global_load_lds_dwordx4 v160, s[98:99]
	s_mov_b32 m0, s61
	s_nop 0
	global_load_lds_dwordx4 v161, s[98:99]
	ds_read_b128 v[240:243], v169
	ds_read_b128 v[244:247], v169 offset:1024
	ds_read_b128 v[248:251], v169 offset:2048
	ds_read_b128 v[228:231], v169 offset:3072
	s_barrier
	s_waitcnt lgkmcnt(3)
	v_mfma_f32_16x16x32_bf16 v[32:35], v[240:243], v[188:191], v[32:35]
	s_waitcnt lgkmcnt(1)
	v_mfma_f32_16x16x32_bf16 v[36:39], v[248:251], v[188:191], v[36:39]
	v_mfma_f32_16x16x32_bf16 v[48:51], v[240:243], v[202:205], v[48:51]
	v_mfma_f32_16x16x32_bf16 v[52:55], v[248:251], v[202:205], v[52:55]
	v_mfma_f32_16x16x32_bf16 v[64:67], v[240:243], v[210:213], v[64:67]
	v_mfma_f32_16x16x32_bf16 v[68:71], v[248:251], v[210:213], v[68:71]
	v_mfma_f32_16x16x32_bf16 v[80:83], v[240:243], v[218:221], v[80:83]
	v_mfma_f32_16x16x32_bf16 v[84:87], v[248:251], v[218:221], v[84:87]
	v_mfma_f32_16x16x32_bf16 v[32:35], v[244:247], v[192:195], v[32:35]
	s_waitcnt lgkmcnt(0)
	v_mfma_f32_16x16x32_bf16 v[36:39], v[228:231], v[192:195], v[36:39]
	v_mfma_f32_16x16x32_bf16 v[48:51], v[244:247], v[206:209], v[48:51]
	v_mfma_f32_16x16x32_bf16 v[52:55], v[228:231], v[206:209], v[52:55]
	v_mfma_f32_16x16x32_bf16 v[64:67], v[244:247], v[214:217], v[64:67]
	v_mfma_f32_16x16x32_bf16 v[68:71], v[228:231], v[214:217], v[68:71]
	v_mfma_f32_16x16x32_bf16 v[80:83], v[244:247], v[236:239], v[80:83]
	v_mfma_f32_16x16x32_bf16 v[84:87], v[228:231], v[236:239], v[84:87]
	s_add_u32 s92, s90, vcc_lo
	s_addc_u32 s93, s91, vcc_hi
	s_barrier
	s_mov_b32 m0, s34
	s_add_u32 s98, s92, s0
	s_addc_u32 s99, s93, s1
	global_load_lds_dwordx4 v160, s[98:99]
	s_mov_b32 m0, s79
	s_nop 0
	global_load_lds_dwordx4 v161, s[98:99]
	ds_read_b128 v[188:191], v166 offset:16384
	ds_read_b128 v[192:195], v166 offset:17408
	ds_read_b128 v[202:205], v165 offset:16384
	ds_read_b128 v[206:209], v165 offset:17408
	ds_read_b128 v[210:213], v163 offset:16384
	ds_read_b128 v[214:217], v163 offset:17408
	ds_read_b128 v[218:221], v162 offset:16384
	ds_read_b128 v[236:239], v162 offset:17408
	s_barrier
	s_waitcnt lgkmcnt(7)
	v_mfma_f32_16x16x32_bf16 v[108:111], v[172:175], v[188:191], v[108:111]
	v_mfma_f32_16x16x32_bf16 v[104:107], v[180:183], v[188:191], v[104:107]
	s_waitcnt lgkmcnt(5)
	v_mfma_f32_16x16x32_bf16 v[124:127], v[172:175], v[202:205], v[124:127]
	v_mfma_f32_16x16x32_bf16 v[120:123], v[180:183], v[202:205], v[120:123]
	s_waitcnt lgkmcnt(3)
	v_mfma_f32_16x16x32_bf16 v[140:143], v[172:175], v[210:213], v[140:143]
	v_mfma_f32_16x16x32_bf16 v[136:139], v[180:183], v[210:213], v[136:139]
	s_waitcnt lgkmcnt(1)
	v_mfma_f32_16x16x32_bf16 v[156:159], v[172:175], v[218:221], v[156:159]
	v_mfma_f32_16x16x32_bf16 v[152:155], v[180:183], v[218:221], v[152:155]
	v_mfma_f32_16x16x32_bf16 v[108:111], v[176:179], v[192:195], v[108:111]
	v_mfma_f32_16x16x32_bf16 v[104:107], v[184:187], v[192:195], v[104:107]
	v_mfma_f32_16x16x32_bf16 v[124:127], v[176:179], v[206:209], v[124:127]
	v_mfma_f32_16x16x32_bf16 v[120:123], v[184:187], v[206:209], v[120:123]
	v_mfma_f32_16x16x32_bf16 v[140:143], v[176:179], v[214:217], v[140:143]
	v_mfma_f32_16x16x32_bf16 v[136:139], v[184:187], v[214:217], v[136:139]
	s_waitcnt lgkmcnt(0)
	v_mfma_f32_16x16x32_bf16 v[156:159], v[176:179], v[236:239], v[156:159]
	v_mfma_f32_16x16x32_bf16 v[152:155], v[184:187], v[236:239], v[152:155]
	s_barrier
	s_add_u32 s96, s82, vcc_lo
	s_addc_u32 s97, s36, vcc_hi
	s_mov_b32 m0, s52
	s_add_u32 s98, s96, s0
	s_addc_u32 s99, s97, s1
	global_load_lds_dwordx4 v160, s[98:99]
	s_mov_b32 m0, s53
	s_nop 0
	global_load_lds_dwordx4 v161, s[98:99]
	s_waitcnt vmcnt(6)
	s_barrier
	v_mfma_f32_16x16x32_bf16 v[96:99], v[240:243], v[188:191], v[96:99]
	v_mfma_f32_16x16x32_bf16 v[100:103], v[248:251], v[188:191], v[100:103]
	v_mfma_f32_16x16x32_bf16 v[112:115], v[240:243], v[202:205], v[112:115]
	v_mfma_f32_16x16x32_bf16 v[116:119], v[248:251], v[202:205], v[116:119]
	v_mfma_f32_16x16x32_bf16 v[128:131], v[240:243], v[210:213], v[128:131]
	v_mfma_f32_16x16x32_bf16 v[132:135], v[248:251], v[210:213], v[132:135]
	v_mfma_f32_16x16x32_bf16 v[144:147], v[240:243], v[218:221], v[144:147]
	v_mfma_f32_16x16x32_bf16 v[148:151], v[248:251], v[218:221], v[148:151]
	v_mfma_f32_16x16x32_bf16 v[96:99], v[244:247], v[192:195], v[96:99]
	v_mfma_f32_16x16x32_bf16 v[100:103], v[228:231], v[192:195], v[100:103]
	v_mfma_f32_16x16x32_bf16 v[112:115], v[244:247], v[206:209], v[112:115]
	v_mfma_f32_16x16x32_bf16 v[116:119], v[228:231], v[206:209], v[116:119]
	v_mfma_f32_16x16x32_bf16 v[128:131], v[244:247], v[214:217], v[128:131]
	v_mfma_f32_16x16x32_bf16 v[132:135], v[228:231], v[214:217], v[132:135]
	v_mfma_f32_16x16x32_bf16 v[144:147], v[244:247], v[236:239], v[144:147]
	v_mfma_f32_16x16x32_bf16 v[148:151], v[228:231], v[236:239], v[148:151]
	s_barrier
	s_mov_b32 m0, s68
	s_add_u32 s98, s8, s0
	s_addc_u32 s99, s9, s1
	global_load_lds_dwordx4 v160, s[98:99]
	s_mov_b32 m0, s69
	s_nop 0
	global_load_lds_dwordx4 v161, s[98:99]
	ds_read_b128 v[172:175], v168
	ds_read_b128 v[176:179], v168 offset:1024
	ds_read_b128 v[180:183], v168 offset:2048
	ds_read_b128 v[184:187], v168 offset:3072
	ds_read_b128 v[188:191], v166 offset:32768
	ds_read_b128 v[192:195], v166 offset:33792
	ds_read_b128 v[202:205], v165 offset:32768
	ds_read_b128 v[206:209], v165 offset:33792
	ds_read_b128 v[210:213], v163 offset:32768
	ds_read_b128 v[214:217], v163 offset:33792
	ds_read_b128 v[218:221], v162 offset:32768
	ds_read_b128 v[228:231], v162 offset:33792
	s_waitcnt lgkmcnt(8)
	s_barrier
	s_waitcnt lgkmcnt(7)
	v_mfma_f32_16x16x32_bf16 v[44:47], v[172:175], v[188:191], v[44:47]
	v_mfma_f32_16x16x32_bf16 v[40:43], v[180:183], v[188:191], v[40:43]
	s_waitcnt lgkmcnt(5)
	v_mfma_f32_16x16x32_bf16 v[60:63], v[172:175], v[202:205], v[60:63]
	v_mfma_f32_16x16x32_bf16 v[56:59], v[180:183], v[202:205], v[56:59]
	s_waitcnt lgkmcnt(3)
	v_mfma_f32_16x16x32_bf16 v[76:79], v[172:175], v[210:213], v[76:79]
	v_mfma_f32_16x16x32_bf16 v[72:75], v[180:183], v[210:213], v[72:75]
	s_waitcnt lgkmcnt(1)
	v_mfma_f32_16x16x32_bf16 v[92:95], v[172:175], v[218:221], v[92:95]
	v_mfma_f32_16x16x32_bf16 v[88:91], v[180:183], v[218:221], v[88:91]
	v_mfma_f32_16x16x32_bf16 v[44:47], v[176:179], v[192:195], v[44:47]
	v_mfma_f32_16x16x32_bf16 v[40:43], v[184:187], v[192:195], v[40:43]
	v_mfma_f32_16x16x32_bf16 v[60:63], v[176:179], v[206:209], v[60:63]
	v_mfma_f32_16x16x32_bf16 v[56:59], v[184:187], v[206:209], v[56:59]
	v_mfma_f32_16x16x32_bf16 v[76:79], v[176:179], v[214:217], v[76:79]
	v_mfma_f32_16x16x32_bf16 v[72:75], v[184:187], v[214:217], v[72:75]
	s_waitcnt lgkmcnt(0)
	v_mfma_f32_16x16x32_bf16 v[92:95], v[176:179], v[228:231], v[92:95]
	v_mfma_f32_16x16x32_bf16 v[88:91], v[184:187], v[228:231], v[88:91]
	s_barrier
	s_mov_b32 m0, s70
	s_add_u32 s98, s28, s30
	s_addc_u32 s99, s29, s31
	global_load_lds_dwordx4 v160, s[98:99]
	s_mov_b32 m0, s71
	s_nop 0
	global_load_lds_dwordx4 v161, s[98:99]
	ds_read_b128 v[236:239], v167
	ds_read_b128 v[240:243], v167 offset:1024
	ds_read_b128 v[244:247], v167 offset:2048
	ds_read_b128 v[248:251], v167 offset:3072
	s_barrier
	s_waitcnt lgkmcnt(3)
	v_mfma_f32_16x16x32_bf16 v[32:35], v[236:239], v[188:191], v[32:35]
	s_waitcnt lgkmcnt(1)
	v_mfma_f32_16x16x32_bf16 v[36:39], v[244:247], v[188:191], v[36:39]
	v_mfma_f32_16x16x32_bf16 v[48:51], v[236:239], v[202:205], v[48:51]
	v_mfma_f32_16x16x32_bf16 v[52:55], v[244:247], v[202:205], v[52:55]
	v_mfma_f32_16x16x32_bf16 v[64:67], v[236:239], v[210:213], v[64:67]
	v_mfma_f32_16x16x32_bf16 v[68:71], v[244:247], v[210:213], v[68:71]
	v_mfma_f32_16x16x32_bf16 v[80:83], v[236:239], v[218:221], v[80:83]
	v_mfma_f32_16x16x32_bf16 v[84:87], v[244:247], v[218:221], v[84:87]
	v_mfma_f32_16x16x32_bf16 v[32:35], v[240:243], v[192:195], v[32:35]
	s_waitcnt lgkmcnt(0)
	v_mfma_f32_16x16x32_bf16 v[36:39], v[248:251], v[192:195], v[36:39]
	v_mfma_f32_16x16x32_bf16 v[48:51], v[240:243], v[206:209], v[48:51]
	v_mfma_f32_16x16x32_bf16 v[52:55], v[248:251], v[206:209], v[52:55]
	v_mfma_f32_16x16x32_bf16 v[64:67], v[240:243], v[214:217], v[64:67]
	v_mfma_f32_16x16x32_bf16 v[68:71], v[248:251], v[214:217], v[68:71]
	v_mfma_f32_16x16x32_bf16 v[80:83], v[240:243], v[228:231], v[80:83]
	v_mfma_f32_16x16x32_bf16 v[84:87], v[248:251], v[228:231], v[84:87]
	v_mov_b32_e32 v222, v161
	s_barrier
	ds_read_b128 v[188:191], v166 offset:49152
	ds_read_b128 v[192:195], v166 offset:50176
	ds_read_b128 v[202:205], v165 offset:49152
	ds_read_b128 v[206:209], v165 offset:50176
	ds_read_b128 v[210:213], v163 offset:49152
	ds_read_b128 v[214:217], v163 offset:50176
	ds_read_b128 v[218:221], v162 offset:49152
	ds_read_b128 v[228:231], v162 offset:50176
	v_mov_b32_e32 v223, v197
	s_mov_b32 m0, s72
	s_add_u32 s98, s92, s30
	s_addc_u32 s99, s93, s31
	global_load_lds_dwordx4 v160, s[98:99]
	s_mov_b32 m0, s73
	s_nop 0
	global_load_lds_dwordx4 v161, s[98:99]
	s_barrier
	s_waitcnt lgkmcnt(7)
	v_mfma_f32_16x16x32_bf16 v[108:111], v[172:175], v[188:191], v[108:111]
	v_mfma_f32_16x16x32_bf16 v[104:107], v[180:183], v[188:191], v[104:107]
	s_waitcnt lgkmcnt(5)
	v_mfma_f32_16x16x32_bf16 v[124:127], v[172:175], v[202:205], v[124:127]
	v_mfma_f32_16x16x32_bf16 v[120:123], v[180:183], v[202:205], v[120:123]
	s_waitcnt lgkmcnt(3)
	v_mfma_f32_16x16x32_bf16 v[140:143], v[172:175], v[210:213], v[140:143]
	v_mfma_f32_16x16x32_bf16 v[136:139], v[180:183], v[210:213], v[136:139]
	s_waitcnt lgkmcnt(1)
	v_mfma_f32_16x16x32_bf16 v[156:159], v[172:175], v[218:221], v[156:159]
	v_mfma_f32_16x16x32_bf16 v[152:155], v[180:183], v[218:221], v[152:155]
	v_mfma_f32_16x16x32_bf16 v[108:111], v[176:179], v[192:195], v[108:111]
	v_mfma_f32_16x16x32_bf16 v[104:107], v[184:187], v[192:195], v[104:107]
	v_mfma_f32_16x16x32_bf16 v[124:127], v[176:179], v[206:209], v[124:127]
	v_mfma_f32_16x16x32_bf16 v[120:123], v[184:187], v[206:209], v[120:123]
	v_mfma_f32_16x16x32_bf16 v[140:143], v[176:179], v[214:217], v[140:143]
	v_mfma_f32_16x16x32_bf16 v[136:139], v[184:187], v[214:217], v[136:139]
	s_waitcnt lgkmcnt(0)
	v_mfma_f32_16x16x32_bf16 v[156:159], v[176:179], v[228:231], v[156:159]
	v_mfma_f32_16x16x32_bf16 v[152:155], v[184:187], v[228:231], v[152:155]
	s_barrier
	v_mov_b32_e32 v196, v160
	s_mov_b32 m0, s75
	s_add_u32 s98, s96, s30
	s_addc_u32 s99, s97, s31
	global_load_lds_dwordx4 v160, s[98:99]
	s_mov_b32 m0, s89
	s_nop 0
	global_load_lds_dwordx4 v161, s[98:99]
	s_waitcnt vmcnt(6)
	s_barrier
	v_mfma_f32_16x16x32_bf16 v[96:99], v[236:239], v[188:191], v[96:99]
	v_mfma_f32_16x16x32_bf16 v[100:103], v[244:247], v[188:191], v[100:103]
	v_mfma_f32_16x16x32_bf16 v[112:115], v[236:239], v[202:205], v[112:115]
	v_mfma_f32_16x16x32_bf16 v[116:119], v[244:247], v[202:205], v[116:119]
	v_mfma_f32_16x16x32_bf16 v[128:131], v[236:239], v[210:213], v[128:131]
	v_mfma_f32_16x16x32_bf16 v[132:135], v[244:247], v[210:213], v[132:135]
	v_mfma_f32_16x16x32_bf16 v[144:147], v[236:239], v[218:221], v[144:147]
	v_mfma_f32_16x16x32_bf16 v[148:151], v[244:247], v[218:221], v[148:151]
	v_mfma_f32_16x16x32_bf16 v[96:99], v[240:243], v[192:195], v[96:99]
	v_mfma_f32_16x16x32_bf16 v[100:103], v[248:251], v[192:195], v[100:103]
	v_mfma_f32_16x16x32_bf16 v[112:115], v[240:243], v[206:209], v[112:115]
	v_mfma_f32_16x16x32_bf16 v[116:119], v[248:251], v[206:209], v[116:119]
	v_mfma_f32_16x16x32_bf16 v[128:131], v[240:243], v[214:217], v[128:131]
	v_mfma_f32_16x16x32_bf16 v[132:135], v[248:251], v[214:217], v[132:135]
	v_mfma_f32_16x16x32_bf16 v[144:147], v[240:243], v[228:231], v[144:147]
	v_mfma_f32_16x16x32_bf16 v[148:151], v[248:251], v[228:231], v[148:151]
	s_add_u32 vcc_lo, vcc_lo, 0x100
	s_addc_u32 vcc_hi, vcc_hi, 0
	s_cmp_lt_u32 s39, s74
	s_barrier
	s_cbranch_scc1 .LBB0_314
	s_add_i32 s34, s33, -1
	s_lshl_b64 s[6:7], s[34:35], 7
	s_add_u32 s6, s84, s6
	s_addc_u32 s7, s85, s7
	s_mov_b32 m0, s40
	ds_read_b128 v[172:175], v170
	ds_read_b128 v[176:179], v170 offset:1024
	ds_read_b128 v[180:183], v170 offset:2048
	ds_read_b128 v[184:187], v170 offset:3072
	ds_read_b128 v[188:191], v166
	ds_read_b128 v[192:195], v166 offset:1024
	ds_read_b128 v[202:205], v165
	ds_read_b128 v[206:209], v165 offset:1024
	ds_read_b128 v[210:213], v163
	ds_read_b128 v[214:217], v163 offset:1024
	ds_read_b128 v[218:221], v162
	ds_read_b128 v[228:231], v162 offset:1024
	s_nop 0
	global_load_lds_dwordx4 v160, s[6:7]
	s_mov_b32 m0, s41
	s_nop 0
	global_load_lds_dwordx4 v161, s[6:7]
	s_barrier
	s_waitcnt lgkmcnt(0)
	s_setprio 1
	s_waitcnt lgkmcnt(0)
	v_mfma_f32_16x16x32_bf16 v[40:43], v[180:183], v[188:191], v[40:43]
	v_mfma_f32_16x16x32_bf16 v[56:59], v[180:183], v[202:205], v[56:59]
	v_mfma_f32_16x16x32_bf16 v[72:75], v[180:183], v[210:213], v[72:75]
	v_mfma_f32_16x16x32_bf16 v[92:95], v[172:175], v[218:221], v[92:95]
	v_mfma_f32_16x16x32_bf16 v[88:91], v[180:183], v[218:221], v[88:91]
	v_mfma_f32_16x16x32_bf16 v[44:47], v[172:175], v[188:191], v[44:47]
	v_mfma_f32_16x16x32_bf16 v[40:43], v[184:187], v[192:195], v[40:43]
	v_mfma_f32_16x16x32_bf16 v[60:63], v[172:175], v[202:205], v[60:63]
	v_mfma_f32_16x16x32_bf16 v[56:59], v[184:187], v[206:209], v[56:59]
	v_mfma_f32_16x16x32_bf16 v[76:79], v[172:175], v[210:213], v[76:79]
	v_mfma_f32_16x16x32_bf16 v[72:75], v[184:187], v[214:217], v[72:75]
	v_mfma_f32_16x16x32_bf16 v[92:95], v[176:179], v[228:231], v[92:95]
	v_mfma_f32_16x16x32_bf16 v[88:91], v[184:187], v[228:231], v[88:91]
	v_mfma_f32_16x16x32_bf16 v[44:47], v[176:179], v[192:195], v[44:47]
	v_mfma_f32_16x16x32_bf16 v[60:63], v[176:179], v[206:209], v[60:63]
	v_mfma_f32_16x16x32_bf16 v[76:79], v[176:179], v[214:217], v[76:79]
	s_setprio 0
	s_barrier
	ds_read_b128 v[236:239], v169
	ds_read_b128 v[240:243], v169 offset:1024
	ds_read_b128 v[244:247], v169 offset:2048
	ds_read_b128 v[248:251], v169 offset:3072
	s_barrier
	s_waitcnt lgkmcnt(0)
	s_setprio 1
	s_waitcnt lgkmcnt(0)
	v_mfma_f32_16x16x32_bf16 v[36:39], v[244:247], v[188:191], v[36:39]
	v_mfma_f32_16x16x32_bf16 v[32:35], v[236:239], v[188:191], v[32:35]
	v_mfma_f32_16x16x32_bf16 v[188:191], v[248:251], v[192:195], v[36:39]
	v_mfma_f32_16x16x32_bf16 v[36:39], v[236:239], v[202:205], v[48:51]
	v_mfma_f32_16x16x32_bf16 v[48:51], v[240:243], v[206:209], v[36:39]
	v_mfma_f32_16x16x32_bf16 v[36:39], v[244:247], v[202:205], v[52:55]
	v_mfma_f32_16x16x32_bf16 v[32:35], v[240:243], v[192:195], v[32:35]
	v_mfma_f32_16x16x32_bf16 v[192:195], v[248:251], v[206:209], v[36:39]
	v_mfma_f32_16x16x32_bf16 v[36:39], v[236:239], v[210:213], v[64:67]
	v_mfma_f32_16x16x32_bf16 v[64:67], v[240:243], v[214:217], v[36:39]
	v_mfma_f32_16x16x32_bf16 v[36:39], v[244:247], v[210:213], v[68:71]
	v_mfma_f32_16x16x32_bf16 v[202:205], v[248:251], v[214:217], v[36:39]
	v_mfma_f32_16x16x32_bf16 v[36:39], v[236:239], v[218:221], v[80:83]
	v_mfma_f32_16x16x32_bf16 v[80:83], v[240:243], v[228:231], v[36:39]
	v_mfma_f32_16x16x32_bf16 v[36:39], v[244:247], v[218:221], v[84:87]
	v_mfma_f32_16x16x32_bf16 v[206:209], v[248:251], v[228:231], v[36:39]
	s_setprio 0
	s_barrier
	s_nop 4
	ds_read_b128 v[36:39], v166 offset:16384
	ds_read_b128 v[52:55], v166 offset:17408
	ds_read_b128 v[68:71], v165 offset:16384
	ds_read_b128 v[84:87], v165 offset:17408
	ds_read_b128 v[210:213], v163 offset:16384
	ds_read_b128 v[214:217], v163 offset:17408
	ds_read_b128 v[218:221], v162 offset:16384
	ds_read_b128 v[228:231], v162 offset:17408
	s_waitcnt vmcnt(4)
	s_barrier
	s_waitcnt lgkmcnt(0)
	s_setprio 1
	s_waitcnt lgkmcnt(0)
	v_mfma_f32_16x16x32_bf16 v[108:111], v[172:175], v[36:39], v[108:111]
	v_mfma_f32_16x16x32_bf16 v[222:225], v[176:179], v[52:55], v[108:111]
	v_mfma_f32_16x16x32_bf16 v[108:111], v[172:175], v[68:71], v[124:127]
	v_mfma_f32_16x16x32_bf16 v[124:127], v[176:179], v[84:87], v[108:111]
	v_mfma_f32_16x16x32_bf16 v[108:111], v[180:183], v[68:71], v[120:123]
	v_mfma_f32_16x16x32_bf16 v[120:123], v[184:187], v[84:87], v[108:111]
	v_mfma_f32_16x16x32_bf16 v[108:111], v[172:175], v[210:213], v[140:143]
	v_mfma_f32_16x16x32_bf16 v[140:143], v[176:179], v[214:217], v[108:111]
	v_mfma_f32_16x16x32_bf16 v[108:111], v[180:183], v[210:213], v[136:139]
	v_mfma_f32_16x16x32_bf16 v[136:139], v[184:187], v[214:217], v[108:111]
	v_mfma_f32_16x16x32_bf16 v[108:111], v[172:175], v[218:221], v[156:159]
	v_mfma_f32_16x16x32_bf16 v[104:107], v[180:183], v[36:39], v[104:107]
	v_mfma_f32_16x16x32_bf16 v[156:159], v[176:179], v[228:231], v[108:111]
	v_mfma_f32_16x16x32_bf16 v[108:111], v[180:183], v[218:221], v[152:155]
	v_mfma_f32_16x16x32_bf16 v[104:107], v[184:187], v[52:55], v[104:107]
	v_mfma_f32_16x16x32_bf16 v[152:155], v[184:187], v[228:231], v[108:111]
	s_setprio 0
	s_setprio 1
	v_mfma_f32_16x16x32_bf16 v[96:99], v[236:239], v[36:39], v[96:99]
	v_mfma_f32_16x16x32_bf16 v[36:39], v[244:247], v[36:39], v[100:103]
	v_mfma_f32_16x16x32_bf16 v[172:175], v[248:251], v[52:55], v[36:39]
	v_mfma_f32_16x16x32_bf16 v[36:39], v[236:239], v[68:71], v[112:115]
	v_mfma_f32_16x16x32_bf16 v[112:115], v[240:243], v[84:87], v[36:39]
	v_mfma_f32_16x16x32_bf16 v[36:39], v[244:247], v[68:71], v[116:119]
	v_mfma_f32_16x16x32_bf16 v[180:183], v[248:251], v[84:87], v[36:39]
	v_mfma_f32_16x16x32_bf16 v[36:39], v[236:239], v[210:213], v[128:131]
	v_mfma_f32_16x16x32_bf16 v[128:131], v[240:243], v[214:217], v[36:39]
	v_mfma_f32_16x16x32_bf16 v[36:39], v[244:247], v[210:213], v[132:135]
	v_mfma_f32_16x16x32_bf16 v[184:187], v[248:251], v[214:217], v[36:39]
	v_mfma_f32_16x16x32_bf16 v[36:39], v[236:239], v[218:221], v[144:147]
	v_mfma_f32_16x16x32_bf16 v[96:99], v[240:243], v[52:55], v[96:99]
	v_mfma_f32_16x16x32_bf16 v[144:147], v[240:243], v[228:231], v[36:39]
	v_mfma_f32_16x16x32_bf16 v[36:39], v[244:247], v[218:221], v[148:151]
	v_mfma_f32_16x16x32_bf16 v[210:213], v[248:251], v[228:231], v[36:39]
	s_setprio 0
	s_barrier
	ds_read_b128 v[148:151], v168
	ds_read_b128 v[214:217], v168 offset:1024
	ds_read_b128 v[218:221], v168 offset:2048
	ds_read_b128 v[228:231], v168 offset:3072
	ds_read_b128 v[100:103], v166 offset:32768
	ds_read_b128 v[108:111], v166 offset:33792
	ds_read_b128 v[116:119], v165 offset:32768
	ds_read_b128 v[132:135], v165 offset:33792
	ds_read_b128 v[236:239], v163 offset:32768
	ds_read_b128 v[240:243], v163 offset:33792
	ds_read_b128 v[244:247], v162 offset:32768
	ds_read_b128 v[248:251], v162 offset:33792
	s_waitcnt vmcnt(2)
	s_barrier
	s_waitcnt lgkmcnt(0)
	s_setprio 1
	s_waitcnt lgkmcnt(0)
	v_mfma_f32_16x16x32_bf16 v[36:39], v[148:151], v[100:103], v[44:47]
	v_mfma_f32_16x16x32_bf16 v[44:47], v[148:151], v[116:119], v[60:63]
	v_mfma_f32_16x16x32_bf16 v[52:55], v[214:217], v[132:135], v[44:47]
	v_mfma_f32_16x16x32_bf16 v[44:47], v[218:221], v[116:119], v[56:59]
	v_mfma_f32_16x16x32_bf16 v[56:59], v[228:231], v[132:135], v[44:47]
	v_mfma_f32_16x16x32_bf16 v[44:47], v[148:151], v[236:239], v[76:79]
	v_mfma_f32_16x16x32_bf16 v[68:71], v[214:217], v[240:243], v[44:47]
	v_mfma_f32_16x16x32_bf16 v[44:47], v[218:221], v[236:239], v[72:75]
	v_mfma_f32_16x16x32_bf16 v[72:75], v[228:231], v[240:243], v[44:47]
	v_mfma_f32_16x16x32_bf16 v[44:47], v[148:151], v[244:247], v[92:95]
	v_mfma_f32_16x16x32_bf16 v[40:43], v[218:221], v[100:103], v[40:43]
	v_mfma_f32_16x16x32_bf16 v[84:87], v[214:217], v[248:251], v[44:47]
	v_mfma_f32_16x16x32_bf16 v[44:47], v[218:221], v[244:247], v[88:91]
	v_mfma_f32_16x16x32_bf16 v[36:39], v[214:217], v[108:111], v[36:39]
	v_mfma_f32_16x16x32_bf16 v[40:43], v[228:231], v[108:111], v[40:43]
	v_mfma_f32_16x16x32_bf16 v[88:91], v[228:231], v[248:251], v[44:47]
	s_setprio 0
	s_barrier
	s_nop 2
	ds_read_b128 v[44:47], v167
	ds_read_b128 v[60:63], v167 offset:1024
	ds_read_b128 v[76:79], v167 offset:2048
	ds_read_b128 v[232:235], v167 offset:3072
	s_waitcnt vmcnt(0)
	s_barrier
	s_waitcnt lgkmcnt(0)
	s_setprio 1
	s_waitcnt lgkmcnt(0)
	v_mfma_f32_16x16x32_bf16 v[92:95], v[76:79], v[100:103], v[188:191]
	v_mfma_f32_16x16x32_bf16 v[176:179], v[232:235], v[108:111], v[92:95]
	v_mfma_f32_16x16x32_bf16 v[92:95], v[76:79], v[116:119], v[192:195]
	v_mfma_f32_16x16x32_bf16 v[32:35], v[44:47], v[100:103], v[32:35]
	v_mfma_f32_16x16x32_bf16 v[48:51], v[44:47], v[116:119], v[48:51]
	v_mfma_f32_16x16x32_bf16 v[168:171], v[232:235], v[132:135], v[92:95]
	v_mfma_f32_16x16x32_bf16 v[64:67], v[44:47], v[236:239], v[64:67]
	v_mfma_f32_16x16x32_bf16 v[92:95], v[76:79], v[236:239], v[202:205]
	v_mfma_f32_16x16x32_bf16 v[80:83], v[44:47], v[244:247], v[80:83]
	v_mfma_f32_16x16x32_bf16 v[100:103], v[76:79], v[244:247], v[206:209]
	v_mfma_f32_16x16x32_bf16 v[32:35], v[60:63], v[108:111], v[32:35]
	v_mfma_f32_16x16x32_bf16 v[48:51], v[60:63], v[132:135], v[48:51]
	v_mfma_f32_16x16x32_bf16 v[64:67], v[60:63], v[240:243], v[64:67]
	v_mfma_f32_16x16x32_bf16 v[92:95], v[232:235], v[240:243], v[92:95]
	v_mfma_f32_16x16x32_bf16 v[80:83], v[60:63], v[248:251], v[80:83]
	v_mfma_f32_16x16x32_bf16 v[108:111], v[232:235], v[248:251], v[100:103]
	s_setprio 0
	s_barrier
	ds_read_b128 v[188:191], v166 offset:49152
	ds_read_b128 v[192:195], v166 offset:50176
	ds_read_b128 v[202:205], v165 offset:49152
	ds_read_b128 v[206:209], v165 offset:50176
	ds_read_b128 v[236:239], v163 offset:49152
	ds_read_b128 v[240:243], v163 offset:50176
	ds_read_b128 v[244:247], v162 offset:49152
	ds_read_b128 v[160:163], v162 offset:50176
	s_barrier
	s_waitcnt lgkmcnt(0)
	s_setprio 1
	s_waitcnt lgkmcnt(0)
	v_mfma_f32_16x16x32_bf16 v[116:119], v[148:151], v[202:205], v[124:127]
	v_mfma_f32_16x16x32_bf16 v[124:127], v[148:151], v[236:239], v[140:143]
	v_mfma_f32_16x16x32_bf16 v[132:135], v[214:217], v[240:243], v[124:127]
	v_mfma_f32_16x16x32_bf16 v[124:127], v[218:221], v[236:239], v[136:139]
	v_mfma_f32_16x16x32_bf16 v[136:139], v[228:231], v[240:243], v[124:127]
	v_mfma_f32_16x16x32_bf16 v[124:127], v[148:151], v[244:247], v[156:159]
	v_mfma_f32_16x16x32_bf16 v[100:103], v[148:151], v[188:191], v[222:225]
	v_mfma_f32_16x16x32_bf16 v[104:107], v[218:221], v[188:191], v[104:107]
	v_mfma_f32_16x16x32_bf16 v[120:123], v[218:221], v[202:205], v[120:123]
	v_mfma_f32_16x16x32_bf16 v[148:151], v[214:217], v[160:163], v[124:127]
	v_mfma_f32_16x16x32_bf16 v[124:127], v[218:221], v[244:247], v[152:155]
	v_mfma_f32_16x16x32_bf16 v[100:103], v[214:217], v[192:195], v[100:103]
	v_mfma_f32_16x16x32_bf16 v[104:107], v[228:231], v[192:195], v[104:107]
	v_mfma_f32_16x16x32_bf16 v[116:119], v[214:217], v[206:209], v[116:119]
	v_mfma_f32_16x16x32_bf16 v[120:123], v[228:231], v[206:209], v[120:123]
	v_mfma_f32_16x16x32_bf16 v[152:155], v[228:231], v[160:163], v[124:127]
	s_setprio 0
	s_setprio 1
	v_mfma_f32_16x16x32_bf16 v[96:99], v[44:47], v[188:191], v[96:99]
	v_mfma_f32_16x16x32_bf16 v[112:115], v[44:47], v[202:205], v[112:115]
	v_mfma_f32_16x16x32_bf16 v[128:131], v[44:47], v[236:239], v[128:131]
	v_mfma_f32_16x16x32_bf16 v[44:47], v[44:47], v[244:247], v[144:147]
	v_mfma_f32_16x16x32_bf16 v[124:127], v[76:79], v[188:191], v[172:175]
	v_mfma_f32_16x16x32_bf16 v[140:143], v[76:79], v[202:205], v[180:183]
	v_mfma_f32_16x16x32_bf16 v[156:159], v[76:79], v[236:239], v[184:187]
	v_mfma_f32_16x16x32_bf16 v[144:147], v[60:63], v[160:163], v[44:47]
	v_mfma_f32_16x16x32_bf16 v[44:47], v[76:79], v[244:247], v[210:213]
	v_mfma_f32_16x16x32_bf16 v[96:99], v[60:63], v[192:195], v[96:99]
	v_mfma_f32_16x16x32_bf16 v[124:127], v[232:235], v[192:195], v[124:127]
	v_mfma_f32_16x16x32_bf16 v[112:115], v[60:63], v[206:209], v[112:115]
	v_mfma_f32_16x16x32_bf16 v[140:143], v[232:235], v[206:209], v[140:143]
	v_mfma_f32_16x16x32_bf16 v[128:131], v[60:63], v[240:243], v[128:131]
	v_mfma_f32_16x16x32_bf16 v[156:159], v[232:235], v[240:243], v[156:159]
	v_mfma_f32_16x16x32_bf16 v[160:163], v[232:235], v[160:163], v[44:47]
	s_setprio 0
	s_movk_i32 s6, 0x100
	v_cmp_gt_u32_e32 vcc, s6, v164
	s_barrier
	s_and_saveexec_b64 s[6:7], vcc
	s_cbranch_execz .LBB0_317
	s_barrier

.LBB0_568:
	s_add_u32 s28, s8, s10
	s_addc_u32 s29, s9, s11
	s_add_i32 s39, s68, 0xc000
	s_mov_b32 m0, s39
	s_add_i32 s38, s68, 0xe000
	s_add_u32 s98, s28, s44
	s_addc_u32 s99, s29, s45
	global_load_lds_dwordx4 v128, s[98:99]
	s_mov_b32 m0, s38
	s_nop 0
	global_load_lds_dwordx4 v130, s[98:99]
	ds_read_b128 v[140:143], v129
	ds_read_b128 v[144:147], v129 offset:1024
	ds_read_b128 v[148:151], v129 offset:2048
	ds_read_b128 v[152:155], v129 offset:3072
	ds_read_b128 v[156:159], v136
	ds_read_b128 v[160:163], v136 offset:1024
	ds_read_b128 v[164:167], v135
	ds_read_b128 v[168:171], v135 offset:1024
	ds_read_b128 v[172:175], v134
	ds_read_b128 v[176:179], v134 offset:1024
	ds_read_b128 v[180:183], v133
	ds_read_b128 v[184:187], v133 offset:1024
	s_waitcnt lgkmcnt(8)
	s_barrier
	s_waitcnt lgkmcnt(7)
	v_mfma_f32_16x16x32_bf16 v[124:127], v[140:143], v[156:159], v[124:127]
	v_mfma_f32_16x16x32_bf16 v[120:123], v[148:151], v[156:159], v[120:123]
	s_waitcnt lgkmcnt(5)
	v_mfma_f32_16x16x32_bf16 v[116:119], v[140:143], v[164:167], v[116:119]
	v_mfma_f32_16x16x32_bf16 v[112:115], v[148:151], v[164:167], v[112:115]
	s_waitcnt lgkmcnt(3)
	v_mfma_f32_16x16x32_bf16 v[108:111], v[140:143], v[172:175], v[108:111]
	v_mfma_f32_16x16x32_bf16 v[104:107], v[148:151], v[172:175], v[104:107]
	s_waitcnt lgkmcnt(1)
	v_mfma_f32_16x16x32_bf16 v[100:103], v[140:143], v[180:183], v[100:103]
	v_mfma_f32_16x16x32_bf16 v[96:99], v[148:151], v[180:183], v[96:99]
	v_mfma_f32_16x16x32_bf16 v[124:127], v[144:147], v[160:163], v[124:127]
	v_mfma_f32_16x16x32_bf16 v[120:123], v[152:155], v[160:163], v[120:123]
	v_mfma_f32_16x16x32_bf16 v[116:119], v[144:147], v[168:171], v[116:119]
	v_mfma_f32_16x16x32_bf16 v[112:115], v[152:155], v[168:171], v[112:115]
	v_mfma_f32_16x16x32_bf16 v[108:111], v[144:147], v[176:179], v[108:111]
	v_mfma_f32_16x16x32_bf16 v[104:107], v[152:155], v[176:179], v[104:107]
	s_waitcnt lgkmcnt(0)
	v_mfma_f32_16x16x32_bf16 v[100:103], v[144:147], v[184:187], v[100:103]
	v_mfma_f32_16x16x32_bf16 v[96:99], v[152:155], v[184:187], v[96:99]
	s_barrier
	s_add_u32 s56, s6, s10
	s_addc_u32 s57, s7, s11
	s_add_i32 m0, s68, 0x10000
	s_add_u32 s98, s56, s0
	s_addc_u32 s99, s57, s1
	global_load_lds_dwordx4 v128, s[98:99]
	s_add_i32 m0, s68, 0x12000
	s_nop 0
	global_load_lds_dwordx4 v130, s[98:99]
	ds_read_b128 v[188:191], v139
	ds_read_b128 v[192:195], v139 offset:1024
	ds_read_b128 v[202:205], v139 offset:2048
	ds_read_b128 v[206:209], v139 offset:3072
	s_barrier
	s_waitcnt lgkmcnt(3)
	v_mfma_f32_16x16x32_bf16 v[92:95], v[188:191], v[156:159], v[92:95]
	s_waitcnt lgkmcnt(1)
	v_mfma_f32_16x16x32_bf16 v[88:91], v[202:205], v[156:159], v[88:91]
	v_mfma_f32_16x16x32_bf16 v[84:87], v[188:191], v[164:167], v[84:87]
	v_mfma_f32_16x16x32_bf16 v[80:83], v[202:205], v[164:167], v[80:83]
	v_mfma_f32_16x16x32_bf16 v[76:79], v[188:191], v[172:175], v[76:79]
	v_mfma_f32_16x16x32_bf16 v[72:75], v[202:205], v[172:175], v[72:75]
	v_mfma_f32_16x16x32_bf16 v[68:71], v[188:191], v[180:183], v[68:71]
	v_mfma_f32_16x16x32_bf16 v[64:67], v[202:205], v[180:183], v[64:67]
	v_mfma_f32_16x16x32_bf16 v[92:95], v[192:195], v[160:163], v[92:95]
	s_waitcnt lgkmcnt(0)
	v_mfma_f32_16x16x32_bf16 v[88:91], v[206:209], v[160:163], v[88:91]
	v_mfma_f32_16x16x32_bf16 v[84:87], v[192:195], v[168:171], v[84:87]
	v_mfma_f32_16x16x32_bf16 v[80:83], v[206:209], v[168:171], v[80:83]
	v_mfma_f32_16x16x32_bf16 v[76:79], v[192:195], v[176:179], v[76:79]
	v_mfma_f32_16x16x32_bf16 v[72:75], v[206:209], v[176:179], v[72:75]
	v_mfma_f32_16x16x32_bf16 v[68:71], v[192:195], v[184:187], v[68:71]
	v_mfma_f32_16x16x32_bf16 v[64:67], v[206:209], v[184:187], v[64:67]
	s_barrier
	s_mov_b32 m0, s68
	s_add_u32 s98, s28, s0
	s_addc_u32 s99, s29, s1
	global_load_lds_dwordx4 v128, s[98:99]
	s_add_i32 m0, s68, 0x2000
	s_nop 0
	global_load_lds_dwordx4 v130, s[98:99]
	ds_read_b128 v[156:159], v136 offset:16384
	ds_read_b128 v[160:163], v136 offset:17408
	ds_read_b128 v[164:167], v135 offset:16384
	ds_read_b128 v[168:171], v135 offset:17408
	ds_read_b128 v[172:175], v134 offset:16384
	ds_read_b128 v[176:179], v134 offset:17408
	ds_read_b128 v[180:183], v133 offset:16384
	ds_read_b128 v[184:187], v133 offset:17408
	s_barrier
	s_waitcnt lgkmcnt(7)
	v_mfma_f32_16x16x32_bf16 v[60:63], v[140:143], v[156:159], v[60:63]
	v_mfma_f32_16x16x32_bf16 v[56:59], v[148:151], v[156:159], v[56:59]
	s_waitcnt lgkmcnt(5)
	v_mfma_f32_16x16x32_bf16 v[52:55], v[140:143], v[164:167], v[52:55]
	v_mfma_f32_16x16x32_bf16 v[48:51], v[148:151], v[164:167], v[48:51]
	s_waitcnt lgkmcnt(3)
	v_mfma_f32_16x16x32_bf16 v[44:47], v[140:143], v[172:175], v[44:47]
	v_mfma_f32_16x16x32_bf16 v[40:43], v[148:151], v[172:175], v[40:43]
	s_waitcnt lgkmcnt(1)
	v_mfma_f32_16x16x32_bf16 v[36:39], v[140:143], v[180:183], v[36:39]
	v_mfma_f32_16x16x32_bf16 v[32:35], v[148:151], v[180:183], v[32:35]
	v_mfma_f32_16x16x32_bf16 v[60:63], v[144:147], v[160:163], v[60:63]
	v_mfma_f32_16x16x32_bf16 v[56:59], v[152:155], v[160:163], v[56:59]
	v_mfma_f32_16x16x32_bf16 v[52:55], v[144:147], v[168:171], v[52:55]
	v_mfma_f32_16x16x32_bf16 v[48:51], v[152:155], v[168:171], v[48:51]
	v_mfma_f32_16x16x32_bf16 v[44:47], v[144:147], v[176:179], v[44:47]
	v_mfma_f32_16x16x32_bf16 v[40:43], v[152:155], v[176:179], v[40:43]
	s_waitcnt lgkmcnt(0)
	v_mfma_f32_16x16x32_bf16 v[36:39], v[144:147], v[184:187], v[36:39]
	v_mfma_f32_16x16x32_bf16 v[32:35], v[152:155], v[184:187], v[32:35]
	s_barrier
	s_add_i32 m0, s68, 0x14000
	s_add_u32 s98, s56, s46
	s_addc_u32 s99, s57, s47
	global_load_lds_dwordx4 v128, s[98:99]
	s_add_i32 m0, s68, 0x16000
	s_nop 0
	global_load_lds_dwordx4 v130, s[98:99]
	s_waitcnt vmcnt(6)
	s_barrier
	v_mfma_f32_16x16x32_bf16 v[28:31], v[188:191], v[156:159], v[28:31]
	v_mfma_f32_16x16x32_bf16 v[24:27], v[202:205], v[156:159], v[24:27]
	v_mfma_f32_16x16x32_bf16 v[20:23], v[188:191], v[164:167], v[20:23]
	v_mfma_f32_16x16x32_bf16 v[16:19], v[202:205], v[164:167], v[16:19]
	v_mfma_f32_16x16x32_bf16 v[12:15], v[188:191], v[172:175], v[12:15]
	v_mfma_f32_16x16x32_bf16 v[8:11], v[202:205], v[172:175], v[8:11]
	v_mfma_f32_16x16x32_bf16 v[4:7], v[188:191], v[180:183], v[4:7]
	v_mfma_f32_16x16x32_bf16 v[0:3], v[202:205], v[180:183], v[0:3]
	v_mfma_f32_16x16x32_bf16 v[28:31], v[192:195], v[160:163], v[28:31]
	v_mfma_f32_16x16x32_bf16 v[24:27], v[206:209], v[160:163], v[24:27]
	v_mfma_f32_16x16x32_bf16 v[20:23], v[192:195], v[168:171], v[20:23]
	v_mfma_f32_16x16x32_bf16 v[16:19], v[206:209], v[168:171], v[16:19]
	v_mfma_f32_16x16x32_bf16 v[12:15], v[192:195], v[176:179], v[12:15]
	v_mfma_f32_16x16x32_bf16 v[8:11], v[206:209], v[176:179], v[8:11]
	v_mfma_f32_16x16x32_bf16 v[4:7], v[192:195], v[184:187], v[4:7]
	v_mfma_f32_16x16x32_bf16 v[0:3], v[206:209], v[184:187], v[0:3]
	s_barrier
	s_add_i32 m0, s68, 0x4000
	s_add_u32 s98, s28, s46
	s_addc_u32 s99, s29, s47
	global_load_lds_dwordx4 v128, s[98:99]
	s_add_i32 m0, s68, 0x6000
	s_nop 0
	global_load_lds_dwordx4 v130, s[98:99]
	ds_read_b128 v[140:143], v138
	ds_read_b128 v[144:147], v138 offset:1024
	ds_read_b128 v[148:151], v138 offset:2048
	ds_read_b128 v[152:155], v138 offset:3072
	ds_read_b128 v[156:159], v136 offset:32768
	ds_read_b128 v[160:163], v136 offset:33792
	ds_read_b128 v[164:167], v135 offset:32768
	ds_read_b128 v[168:171], v135 offset:33792
	ds_read_b128 v[172:175], v134 offset:32768
	ds_read_b128 v[176:179], v134 offset:33792
	ds_read_b128 v[180:183], v133 offset:32768
	ds_read_b128 v[184:187], v133 offset:33792
	s_waitcnt lgkmcnt(8)
	s_barrier
	s_waitcnt lgkmcnt(7)
	v_mfma_f32_16x16x32_bf16 v[124:127], v[140:143], v[156:159], v[124:127]
	v_mfma_f32_16x16x32_bf16 v[120:123], v[148:151], v[156:159], v[120:123]
	s_waitcnt lgkmcnt(5)
	v_mfma_f32_16x16x32_bf16 v[116:119], v[140:143], v[164:167], v[116:119]
	v_mfma_f32_16x16x32_bf16 v[112:115], v[148:151], v[164:167], v[112:115]
	s_waitcnt lgkmcnt(3)
	v_mfma_f32_16x16x32_bf16 v[108:111], v[140:143], v[172:175], v[108:111]
	v_mfma_f32_16x16x32_bf16 v[104:107], v[148:151], v[172:175], v[104:107]
	s_waitcnt lgkmcnt(1)
	v_mfma_f32_16x16x32_bf16 v[100:103], v[140:143], v[180:183], v[100:103]
	v_mfma_f32_16x16x32_bf16 v[96:99], v[148:151], v[180:183], v[96:99]
	v_mfma_f32_16x16x32_bf16 v[124:127], v[144:147], v[160:163], v[124:127]
	v_mfma_f32_16x16x32_bf16 v[120:123], v[152:155], v[160:163], v[120:123]
	v_mfma_f32_16x16x32_bf16 v[116:119], v[144:147], v[168:171], v[116:119]
	v_mfma_f32_16x16x32_bf16 v[112:115], v[152:155], v[168:171], v[112:115]
	v_mfma_f32_16x16x32_bf16 v[108:111], v[144:147], v[176:179], v[108:111]
	v_mfma_f32_16x16x32_bf16 v[104:107], v[152:155], v[176:179], v[104:107]
	s_waitcnt lgkmcnt(0)
	v_mfma_f32_16x16x32_bf16 v[100:103], v[144:147], v[184:187], v[100:103]
	v_mfma_f32_16x16x32_bf16 v[96:99], v[152:155], v[184:187], v[96:99]
	s_barrier
	s_mov_b32 m0, s69
	s_add_u32 s98, s56, s30
	s_addc_u32 s99, s57, s31
	global_load_lds_dwordx4 v128, s[98:99]
	s_mov_b32 m0, s70
	s_nop 0
	global_load_lds_dwordx4 v130, s[98:99]
	ds_read_b128 v[188:191], v137
	ds_read_b128 v[192:195], v137 offset:1024
	ds_read_b128 v[202:205], v137 offset:2048
	ds_read_b128 v[206:209], v137 offset:3072
	s_barrier
	s_waitcnt lgkmcnt(3)
	v_mfma_f32_16x16x32_bf16 v[92:95], v[188:191], v[156:159], v[92:95]
	s_waitcnt lgkmcnt(1)
	v_mfma_f32_16x16x32_bf16 v[88:91], v[202:205], v[156:159], v[88:91]
	v_mfma_f32_16x16x32_bf16 v[84:87], v[188:191], v[164:167], v[84:87]
	v_mfma_f32_16x16x32_bf16 v[80:83], v[202:205], v[164:167], v[80:83]
	v_mfma_f32_16x16x32_bf16 v[76:79], v[188:191], v[172:175], v[76:79]
	v_mfma_f32_16x16x32_bf16 v[72:75], v[202:205], v[172:175], v[72:75]
	v_mfma_f32_16x16x32_bf16 v[68:71], v[188:191], v[180:183], v[68:71]
	v_mfma_f32_16x16x32_bf16 v[64:67], v[202:205], v[180:183], v[64:67]
	v_mfma_f32_16x16x32_bf16 v[92:95], v[192:195], v[160:163], v[92:95]
	s_waitcnt lgkmcnt(0)
	v_mfma_f32_16x16x32_bf16 v[88:91], v[206:209], v[160:163], v[88:91]
	v_mfma_f32_16x16x32_bf16 v[84:87], v[192:195], v[168:171], v[84:87]
	v_mfma_f32_16x16x32_bf16 v[80:83], v[206:209], v[168:171], v[80:83]
	v_mfma_f32_16x16x32_bf16 v[76:79], v[192:195], v[176:179], v[76:79]
	v_mfma_f32_16x16x32_bf16 v[72:75], v[206:209], v[176:179], v[72:75]
	v_mfma_f32_16x16x32_bf16 v[68:71], v[192:195], v[184:187], v[68:71]
	v_mfma_f32_16x16x32_bf16 v[64:67], v[206:209], v[184:187], v[64:67]
	v_mov_b32_e32 v210, v130
	s_barrier
	ds_read_b128 v[156:159], v136 offset:49152
	ds_read_b128 v[160:163], v136 offset:50176
	ds_read_b128 v[164:167], v135 offset:49152
	ds_read_b128 v[168:171], v135 offset:50176
	ds_read_b128 v[172:175], v134 offset:49152
	ds_read_b128 v[176:179], v134 offset:50176
	ds_read_b128 v[180:183], v133 offset:49152
	ds_read_b128 v[184:187], v133 offset:50176
	v_mov_b32_e32 v211, v197
	s_mov_b32 m0, s71
	s_add_u32 s98, s28, s30
	s_addc_u32 s99, s29, s31
	global_load_lds_dwordx4 v128, s[98:99]
	s_mov_b32 m0, s33
	s_nop 0
	global_load_lds_dwordx4 v130, s[98:99]
	s_barrier
	s_waitcnt lgkmcnt(7)
	v_mfma_f32_16x16x32_bf16 v[60:63], v[140:143], v[156:159], v[60:63]
	v_mfma_f32_16x16x32_bf16 v[56:59], v[148:151], v[156:159], v[56:59]
	s_waitcnt lgkmcnt(5)
	v_mfma_f32_16x16x32_bf16 v[52:55], v[140:143], v[164:167], v[52:55]
	v_mfma_f32_16x16x32_bf16 v[48:51], v[148:151], v[164:167], v[48:51]
	s_waitcnt lgkmcnt(3)
	v_mfma_f32_16x16x32_bf16 v[44:47], v[140:143], v[172:175], v[44:47]
	v_mfma_f32_16x16x32_bf16 v[40:43], v[148:151], v[172:175], v[40:43]
	s_waitcnt lgkmcnt(1)
	v_mfma_f32_16x16x32_bf16 v[36:39], v[140:143], v[180:183], v[36:39]
	v_mfma_f32_16x16x32_bf16 v[32:35], v[148:151], v[180:183], v[32:35]
	v_mfma_f32_16x16x32_bf16 v[60:63], v[144:147], v[160:163], v[60:63]
	v_mfma_f32_16x16x32_bf16 v[56:59], v[152:155], v[160:163], v[56:59]
	v_mfma_f32_16x16x32_bf16 v[52:55], v[144:147], v[168:171], v[52:55]
	v_mfma_f32_16x16x32_bf16 v[48:51], v[152:155], v[168:171], v[48:51]
	v_mfma_f32_16x16x32_bf16 v[44:47], v[144:147], v[176:179], v[44:47]
	v_mfma_f32_16x16x32_bf16 v[40:43], v[152:155], v[176:179], v[40:43]
	s_waitcnt lgkmcnt(0)
	v_mfma_f32_16x16x32_bf16 v[36:39], v[144:147], v[184:187], v[36:39]
	v_mfma_f32_16x16x32_bf16 v[32:35], v[152:155], v[184:187], v[32:35]
	s_barrier
	v_mov_b32_e32 v196, v128
	s_mov_b32 m0, s72
	s_add_u32 s98, s56, s48
	s_addc_u32 s99, s57, s49
	global_load_lds_dwordx4 v128, s[98:99]
	s_mov_b32 m0, s36
	s_nop 0
	global_load_lds_dwordx4 v130, s[98:99]
	s_waitcnt vmcnt(6)
	s_barrier
	v_mfma_f32_16x16x32_bf16 v[28:31], v[188:191], v[156:159], v[28:31]
	v_mfma_f32_16x16x32_bf16 v[24:27], v[202:205], v[156:159], v[24:27]
	v_mfma_f32_16x16x32_bf16 v[20:23], v[188:191], v[164:167], v[20:23]
	v_mfma_f32_16x16x32_bf16 v[16:19], v[202:205], v[164:167], v[16:19]
	v_mfma_f32_16x16x32_bf16 v[12:15], v[188:191], v[172:175], v[12:15]
	v_mfma_f32_16x16x32_bf16 v[8:11], v[202:205], v[172:175], v[8:11]
	v_mfma_f32_16x16x32_bf16 v[4:7], v[188:191], v[180:183], v[4:7]
	v_mfma_f32_16x16x32_bf16 v[0:3], v[202:205], v[180:183], v[0:3]
	v_mfma_f32_16x16x32_bf16 v[28:31], v[192:195], v[160:163], v[28:31]
	v_mfma_f32_16x16x32_bf16 v[24:27], v[206:209], v[160:163], v[24:27]
	v_mfma_f32_16x16x32_bf16 v[20:23], v[192:195], v[168:171], v[20:23]
	v_mfma_f32_16x16x32_bf16 v[16:19], v[206:209], v[168:171], v[16:19]
	v_mfma_f32_16x16x32_bf16 v[12:15], v[192:195], v[176:179], v[12:15]
	v_mfma_f32_16x16x32_bf16 v[8:11], v[206:209], v[176:179], v[8:11]
	v_mfma_f32_16x16x32_bf16 v[4:7], v[192:195], v[184:187], v[4:7]
	v_mfma_f32_16x16x32_bf16 v[0:3], v[206:209], v[184:187], v[0:3]
	s_add_i32 s37, s37, 2
	s_add_u32 s10, s10, 0x100
	s_addc_u32 s11, s11, 0
	s_cmp_lt_u32 s37, 28
	s_barrier
	s_cbranch_scc1 .LBB0_568
	s_lshl_b64 s[4:5], s[4:5], 12
	s_add_u32 s4, s67, s4
	s_addc_u32 s5, s53, s5
	ds_read_b128 v[140:143], v129
	ds_read_b128 v[144:147], v129 offset:1024
	ds_read_b128 v[148:151], v129 offset:2048
	ds_read_b128 v[152:155], v129 offset:3072
	ds_read_b128 v[156:159], v136
	ds_read_b128 v[160:163], v136 offset:1024
	ds_read_b128 v[164:167], v135
	ds_read_b128 v[168:171], v135 offset:1024
	ds_read_b128 v[172:175], v134
	ds_read_b128 v[176:179], v134 offset:1024
	ds_read_b128 v[180:183], v133
	ds_read_b128 v[184:187], v133 offset:1024
	v_mov_b32_e32 v129, v197
	v_lshl_add_u64 v[128:129], s[4:5], 0, v[128:129]
	s_mov_b64 s[6:7], 0xf80
	s_mov_b32 m0, s39
	v_lshl_add_u64 v[128:129], v[128:129], 0, s[6:7]
	v_mov_b32_e32 v131, v197
	global_load_lds_dwordx4 v[128:129], off
	v_lshl_add_u64 v[128:129], s[4:5], 0, v[130:131]
	v_lshl_add_u64 v[128:129], v[128:129], 0, s[6:7]
	s_mov_b32 m0, s38
	s_nop 0
	global_load_lds_dwordx4 v[128:129], off
	s_barrier
	s_waitcnt lgkmcnt(0)
	s_setprio 1
	s_waitcnt lgkmcnt(0)
	v_mfma_f32_16x16x32_bf16 v[124:127], v[140:143], v[156:159], v[124:127]
	v_mfma_f32_16x16x32_bf16 v[120:123], v[148:151], v[156:159], v[120:123]
	v_mfma_f32_16x16x32_bf16 v[116:119], v[140:143], v[164:167], v[116:119]
	v_mfma_f32_16x16x32_bf16 v[112:115], v[148:151], v[164:167], v[112:115]
	v_mfma_f32_16x16x32_bf16 v[100:103], v[140:143], v[180:183], v[100:103]
	v_mfma_f32_16x16x32_bf16 v[96:99], v[148:151], v[180:183], v[96:99]
	v_mfma_f32_16x16x32_bf16 v[124:127], v[144:147], v[160:163], v[124:127]
	v_mfma_f32_16x16x32_bf16 v[120:123], v[152:155], v[160:163], v[120:123]
	v_mfma_f32_16x16x32_bf16 v[116:119], v[144:147], v[168:171], v[116:119]
	v_mfma_f32_16x16x32_bf16 v[112:115], v[152:155], v[168:171], v[112:115]
	v_mfma_f32_16x16x32_bf16 v[108:111], v[140:143], v[172:175], v[108:111]
	v_mfma_f32_16x16x32_bf16 v[104:107], v[148:151], v[172:175], v[104:107]
	v_mfma_f32_16x16x32_bf16 v[100:103], v[144:147], v[184:187], v[100:103]
	v_mfma_f32_16x16x32_bf16 v[96:99], v[152:155], v[184:187], v[96:99]
	v_mfma_f32_16x16x32_bf16 v[128:131], v[144:147], v[176:179], v[108:111]
	v_mfma_f32_16x16x32_bf16 v[188:191], v[152:155], v[176:179], v[104:107]
	s_setprio 0
	s_barrier
	s_nop 1
	ds_read_b128 v[104:107], v139
	ds_read_b128 v[108:111], v139 offset:1024
	ds_read_b128 v[192:195], v139 offset:2048
	ds_read_b128 v[202:205], v139 offset:3072
	s_barrier
	s_waitcnt lgkmcnt(0)
	s_setprio 1
	s_waitcnt lgkmcnt(0)
	v_mfma_f32_16x16x32_bf16 v[84:87], v[104:107], v[164:167], v[84:87]
	v_mfma_f32_16x16x32_bf16 v[80:83], v[192:195], v[164:167], v[80:83]
	v_mfma_f32_16x16x32_bf16 v[68:71], v[104:107], v[180:183], v[68:71]
	v_mfma_f32_16x16x32_bf16 v[64:67], v[192:195], v[180:183], v[64:67]
	v_mfma_f32_16x16x32_bf16 v[92:95], v[104:107], v[156:159], v[92:95]
	v_mfma_f32_16x16x32_bf16 v[88:91], v[192:195], v[156:159], v[88:91]
	v_mfma_f32_16x16x32_bf16 v[84:87], v[108:111], v[168:171], v[84:87]
	v_mfma_f32_16x16x32_bf16 v[80:83], v[202:205], v[168:171], v[80:83]
	v_mfma_f32_16x16x32_bf16 v[76:79], v[104:107], v[172:175], v[76:79]
	v_mfma_f32_16x16x32_bf16 v[72:75], v[192:195], v[172:175], v[72:75]
	v_mfma_f32_16x16x32_bf16 v[68:71], v[108:111], v[184:187], v[68:71]
	v_mfma_f32_16x16x32_bf16 v[64:67], v[202:205], v[184:187], v[64:67]
	v_mfma_f32_16x16x32_bf16 v[206:209], v[108:111], v[160:163], v[92:95]
	v_mfma_f32_16x16x32_bf16 v[156:159], v[202:205], v[160:163], v[88:91]
	v_mfma_f32_16x16x32_bf16 v[160:163], v[108:111], v[176:179], v[76:79]
	v_mfma_f32_16x16x32_bf16 v[164:167], v[202:205], v[176:179], v[72:75]
	s_setprio 0
	s_barrier
	s_nop 0
	ds_read_b128 v[72:75], v136 offset:16384
	ds_read_b128 v[76:79], v136 offset:17408
	ds_read_b128 v[88:91], v135 offset:16384
	ds_read_b128 v[92:95], v135 offset:17408
	ds_read_b128 v[168:171], v134 offset:16384
	ds_read_b128 v[172:175], v134 offset:17408
	ds_read_b128 v[176:179], v133 offset:16384
	ds_read_b128 v[180:183], v133 offset:17408
	s_waitcnt vmcnt(4)
	s_barrier
	s_waitcnt lgkmcnt(0)
	s_setprio 1
	s_waitcnt lgkmcnt(0)
	v_mfma_f32_16x16x32_bf16 v[60:63], v[140:143], v[72:75], v[60:63]
	v_mfma_f32_16x16x32_bf16 v[56:59], v[148:151], v[72:75], v[56:59]
	v_mfma_f32_16x16x32_bf16 v[52:55], v[140:143], v[88:91], v[52:55]
	v_mfma_f32_16x16x32_bf16 v[48:51], v[148:151], v[88:91], v[48:51]
	v_mfma_f32_16x16x32_bf16 v[36:39], v[140:143], v[176:179], v[36:39]
	v_mfma_f32_16x16x32_bf16 v[32:35], v[148:151], v[176:179], v[32:35]
	v_mfma_f32_16x16x32_bf16 v[60:63], v[144:147], v[76:79], v[60:63]
	v_mfma_f32_16x16x32_bf16 v[56:59], v[152:155], v[76:79], v[56:59]
	v_mfma_f32_16x16x32_bf16 v[52:55], v[144:147], v[92:95], v[52:55]
	v_mfma_f32_16x16x32_bf16 v[48:51], v[152:155], v[92:95], v[48:51]
	v_mfma_f32_16x16x32_bf16 v[44:47], v[140:143], v[168:171], v[44:47]
	v_mfma_f32_16x16x32_bf16 v[40:43], v[148:151], v[168:171], v[40:43]
	v_mfma_f32_16x16x32_bf16 v[36:39], v[144:147], v[180:183], v[36:39]
	v_mfma_f32_16x16x32_bf16 v[32:35], v[152:155], v[180:183], v[32:35]
	v_mfma_f32_16x16x32_bf16 v[184:187], v[144:147], v[172:175], v[44:47]
	v_mfma_f32_16x16x32_bf16 v[210:213], v[152:155], v[172:175], v[40:43]
	s_setprio 0
	s_setprio 1
	v_mfma_f32_16x16x32_bf16 v[20:23], v[104:107], v[88:91], v[20:23]
	v_mfma_f32_16x16x32_bf16 v[16:19], v[192:195], v[88:91], v[16:19]
	v_mfma_f32_16x16x32_bf16 v[4:7], v[104:107], v[176:179], v[4:7]
	v_mfma_f32_16x16x32_bf16 v[0:3], v[192:195], v[176:179], v[0:3]
	v_mfma_f32_16x16x32_bf16 v[28:31], v[104:107], v[72:75], v[28:31]
	v_mfma_f32_16x16x32_bf16 v[24:27], v[192:195], v[72:75], v[24:27]
	v_mfma_f32_16x16x32_bf16 v[20:23], v[108:111], v[92:95], v[20:23]
	v_mfma_f32_16x16x32_bf16 v[16:19], v[202:205], v[92:95], v[16:19]
	v_mfma_f32_16x16x32_bf16 v[12:15], v[104:107], v[168:171], v[12:15]
	v_mfma_f32_16x16x32_bf16 v[8:11], v[192:195], v[168:171], v[8:11]
	v_mfma_f32_16x16x32_bf16 v[4:7], v[108:111], v[180:183], v[4:7]
	v_mfma_f32_16x16x32_bf16 v[0:3], v[202:205], v[180:183], v[0:3]
	v_mfma_f32_16x16x32_bf16 v[140:143], v[108:111], v[76:79], v[28:31]
	v_mfma_f32_16x16x32_bf16 v[144:147], v[202:205], v[76:79], v[24:27]
	v_mfma_f32_16x16x32_bf16 v[148:151], v[108:111], v[172:175], v[12:15]
	v_mfma_f32_16x16x32_bf16 v[152:155], v[202:205], v[172:175], v[8:11]
	s_setprio 0
	s_barrier
	s_nop 0
	ds_read_b128 v[8:11], v138
	ds_read_b128 v[12:15], v138 offset:1024
	ds_read_b128 v[168:171], v138 offset:2048
	ds_read_b128 v[172:175], v138 offset:3072
	ds_read_b128 v[24:27], v136 offset:32768
	ds_read_b128 v[28:31], v136 offset:33792
	ds_read_b128 v[40:43], v135 offset:32768
	ds_read_b128 v[44:47], v135 offset:33792
	ds_read_b128 v[176:179], v134 offset:32768
	ds_read_b128 v[180:183], v134 offset:33792
	ds_read_b128 v[192:195], v133 offset:32768
	ds_read_b128 v[202:205], v133 offset:33792
	s_waitcnt vmcnt(2)
	s_barrier
	s_waitcnt lgkmcnt(0)
	s_setprio 1
	s_waitcnt lgkmcnt(0)
	v_mfma_f32_16x16x32_bf16 v[72:75], v[8:11], v[24:27], v[124:127]
	v_mfma_f32_16x16x32_bf16 v[124:127], v[12:15], v[28:31], v[72:75]
	v_mfma_f32_16x16x32_bf16 v[72:75], v[168:171], v[24:27], v[120:123]
	v_mfma_f32_16x16x32_bf16 v[120:123], v[172:175], v[28:31], v[72:75]
	v_mfma_f32_16x16x32_bf16 v[72:75], v[8:11], v[40:43], v[116:119]
	v_mfma_f32_16x16x32_bf16 v[108:111], v[12:15], v[44:47], v[72:75]
	v_mfma_f32_16x16x32_bf16 v[72:75], v[168:171], v[40:43], v[112:115]
	v_mfma_f32_16x16x32_bf16 v[104:107], v[172:175], v[44:47], v[72:75]
	v_mfma_f32_16x16x32_bf16 v[72:75], v[8:11], v[176:179], v[128:131]
	v_mfma_f32_16x16x32_bf16 v[92:95], v[12:15], v[180:183], v[72:75]
	v_mfma_f32_16x16x32_bf16 v[72:75], v[168:171], v[176:179], v[188:191]
	v_mfma_f32_16x16x32_bf16 v[88:91], v[172:175], v[180:183], v[72:75]
	v_mfma_f32_16x16x32_bf16 v[72:75], v[8:11], v[192:195], v[100:103]
	v_mfma_f32_16x16x32_bf16 v[76:79], v[12:15], v[202:205], v[72:75]
	v_mfma_f32_16x16x32_bf16 v[72:75], v[168:171], v[192:195], v[96:99]
	v_mfma_f32_16x16x32_bf16 v[72:75], v[172:175], v[202:205], v[72:75]
	s_setprio 0
	s_barrier
	ds_read_b128 v[128:131], v137
	ds_read_b128 v[188:191], v137 offset:1024
	ds_read_b128 v[214:217], v137 offset:2048
	ds_read_b128 v[218:221], v137 offset:3072
	s_waitcnt vmcnt(0)
	s_barrier
	s_waitcnt lgkmcnt(0)
	s_setprio 1
	s_waitcnt lgkmcnt(0)
	v_mfma_f32_16x16x32_bf16 v[96:99], v[128:131], v[24:27], v[206:209]
	v_mfma_f32_16x16x32_bf16 v[24:27], v[214:217], v[24:27], v[156:159]
	v_mfma_f32_16x16x32_bf16 v[112:115], v[218:221], v[28:31], v[24:27]
	v_mfma_f32_16x16x32_bf16 v[24:27], v[128:131], v[40:43], v[84:87]
	v_mfma_f32_16x16x32_bf16 v[100:103], v[188:191], v[44:47], v[24:27]
	v_mfma_f32_16x16x32_bf16 v[24:27], v[214:217], v[40:43], v[80:83]
	v_mfma_f32_16x16x32_bf16 v[116:119], v[188:191], v[28:31], v[96:99]
	v_mfma_f32_16x16x32_bf16 v[96:99], v[218:221], v[44:47], v[24:27]
	v_mfma_f32_16x16x32_bf16 v[24:27], v[128:131], v[176:179], v[160:163]
	v_mfma_f32_16x16x32_bf16 v[84:87], v[188:191], v[180:183], v[24:27]
	v_mfma_f32_16x16x32_bf16 v[24:27], v[214:217], v[176:179], v[164:167]
	v_mfma_f32_16x16x32_bf16 v[80:83], v[218:221], v[180:183], v[24:27]
	v_mfma_f32_16x16x32_bf16 v[24:27], v[128:131], v[192:195], v[68:71]
	v_mfma_f32_16x16x32_bf16 v[68:71], v[188:191], v[202:205], v[24:27]
	v_mfma_f32_16x16x32_bf16 v[24:27], v[214:217], v[192:195], v[64:67]
	v_mfma_f32_16x16x32_bf16 v[64:67], v[218:221], v[202:205], v[24:27]
	s_setprio 0
	s_barrier
	ds_read_b128 v[156:159], v136 offset:49152
	ds_read_b128 v[136:139], v136 offset:50176
	ds_read_b128 v[160:163], v135 offset:49152
	ds_read_b128 v[164:167], v135 offset:50176
	ds_read_b128 v[176:179], v134 offset:49152
	ds_read_b128 v[180:183], v134 offset:50176
	ds_read_b128 v[192:195], v133 offset:49152
	ds_read_b128 v[202:205], v133 offset:50176
	s_barrier
	s_waitcnt lgkmcnt(0)
	s_setprio 1
	s_waitcnt lgkmcnt(0)
	v_mfma_f32_16x16x32_bf16 v[24:27], v[8:11], v[156:159], v[60:63]
	v_mfma_f32_16x16x32_bf16 v[60:63], v[12:15], v[136:139], v[24:27]
	v_mfma_f32_16x16x32_bf16 v[24:27], v[168:171], v[156:159], v[56:59]
	v_mfma_f32_16x16x32_bf16 v[56:59], v[172:175], v[136:139], v[24:27]
	v_mfma_f32_16x16x32_bf16 v[24:27], v[8:11], v[160:163], v[52:55]
	v_mfma_f32_16x16x32_bf16 v[44:47], v[12:15], v[164:167], v[24:27]
	v_mfma_f32_16x16x32_bf16 v[24:27], v[168:171], v[160:163], v[48:51]
	v_mfma_f32_16x16x32_bf16 v[40:43], v[172:175], v[164:167], v[24:27]
	v_mfma_f32_16x16x32_bf16 v[24:27], v[8:11], v[176:179], v[184:187]
	v_mfma_f32_16x16x32_bf16 v[8:11], v[8:11], v[192:195], v[36:39]
	v_mfma_f32_16x16x32_bf16 v[28:31], v[12:15], v[180:183], v[24:27]
	v_mfma_f32_16x16x32_bf16 v[24:27], v[168:171], v[176:179], v[210:213]
	v_mfma_f32_16x16x32_bf16 v[12:15], v[12:15], v[202:205], v[8:11]
	v_mfma_f32_16x16x32_bf16 v[8:11], v[168:171], v[192:195], v[32:35]
	v_mfma_f32_16x16x32_bf16 v[24:27], v[172:175], v[180:183], v[24:27]
	v_mfma_f32_16x16x32_bf16 v[8:11], v[172:175], v[202:205], v[8:11]
	s_setprio 0
	s_setprio 1
	v_mfma_f32_16x16x32_bf16 v[32:35], v[128:131], v[156:159], v[140:143]
	v_mfma_f32_16x16x32_bf16 v[52:55], v[188:191], v[136:139], v[32:35]
	v_mfma_f32_16x16x32_bf16 v[32:35], v[214:217], v[156:159], v[144:147]
	v_mfma_f32_16x16x32_bf16 v[16:19], v[214:217], v[160:163], v[16:19]
	v_mfma_f32_16x16x32_bf16 v[48:51], v[218:221], v[136:139], v[32:35]
	v_mfma_f32_16x16x32_bf16 v[20:23], v[128:131], v[160:163], v[20:23]
	v_mfma_f32_16x16x32_bf16 v[32:35], v[218:221], v[164:167], v[16:19]
	v_mfma_f32_16x16x32_bf16 v[16:19], v[128:131], v[176:179], v[148:151]
	v_mfma_f32_16x16x32_bf16 v[36:39], v[188:191], v[164:167], v[20:23]
	v_mfma_f32_16x16x32_bf16 v[20:23], v[188:191], v[180:183], v[16:19]
	v_mfma_f32_16x16x32_bf16 v[16:19], v[214:217], v[176:179], v[152:155]
	v_mfma_f32_16x16x32_bf16 v[4:7], v[128:131], v[192:195], v[4:7]
	v_mfma_f32_16x16x32_bf16 v[0:3], v[214:217], v[192:195], v[0:3]
	v_mfma_f32_16x16x32_bf16 v[16:19], v[218:221], v[180:183], v[16:19]
	v_mfma_f32_16x16x32_bf16 v[4:7], v[188:191], v[202:205], v[4:7]
	v_mfma_f32_16x16x32_bf16 v[0:3], v[218:221], v[202:205], v[0:3]
	s_setprio 0
	s_movk_i32 s4, 0x100
	v_cmp_gt_u32_e32 vcc, s4, v132
	s_barrier
	s_and_saveexec_b64 s[4:5], vcc
	s_cbranch_execz .LBB0_571
	s_barrier
